# EV-IN/OD-IN scale epilogues: 8 serialized global ssq loads replaced by LDS reads of rows prefetched by LDS-DMA in the K-loop
# speedup vs baseline: 1.0300x; 1.0057x over previous
; #define PG8_STAGE(bufoff, gbase, voff) do { _Pragma("unroll") for (int _i = 0; _i < 2; ++_i) \
;         __builtin_amdgcn_global_load_lds((const unsigned*)((const char*)(gbase) + (voff)[_i]), (PG8_LAS unsigned*)(lds + (bufoff) + ldsw + _i * 8192), 16, 0, 0); } while (0)
; #define PG8_LDA(dst, b, h) do { _Pragma("unroll") for (int m = 0; m < 4; ++m) _Pragma("unroll") for (int k = 0; k < 2; ++k) dst[m][k] = *(const PG8_LAS bf16x8*)(lds + PG8_SA(b, h) + aoff + m * 2048 + k * 1024); } while (0)
; #define PG8_LDB(dst, b, h) do { _Pragma("unroll") for (int n = 0; n < 2; ++n) _Pragma("unroll") for (int k = 0; k < 2; ++k) dst[n][k] = *(const PG8_LAS bf16x8*)(lds + PG8_SB(b, h) + boff + n * 2048 + k * 1024); } while (0)
; #define PG8_MMA(ai, bj, At, Bt) do { __builtin_amdgcn_s_setprio(1); _Pragma("unroll") for (int m = 0; m < 4; ++m) _Pragma("unroll") for (int n = 0; n < 2; ++n) _Pragma("unroll") for (int k = 0; k < 2; ++k) \
;         acc[ai][bj][m][n] = __builtin_amdgcn_mfma_f32_16x16x32_bf16(Bt[n][k], At[m][k], acc[ai][bj][m][n], 0, 0, 0); __builtin_amdgcn_s_setprio(0); } while (0)
; #define PG8_WAIT_V(n) asm volatile("s_waitcnt vmcnt(" #n ")" ::: "memory")
; #define PG8_WAIT_L(n) asm volatile("s_waitcnt lgkmcnt(" #n ")" ::: "memory")
; template <class Epi, class Sched, bool ALIGN_EPI = false, bool SP2 = false>
; __device__ __forceinline__ void gemm_phase(PG8_LAS unsigned char* lds, const Gemm g, const Sched& S, const Epi& E) {
;     ...
;             const bool last = (t == nt - 2);
;             const char* a1 = cA + (size_t)(t + 1) * kstep;
;             const char* a2 = last ? nA : cA + (size_t)(t + 2) * kstep; const char* b2 = last ? nB : cB + (size_t)(t + 2) * kstep;
;             const char* a3 = a2 + kstep; const char* b3 = b2 + kstep;
;             if (last && has_next) S.a_ready(nxt);
;             if constexpr (SP2) {
;             PG8_LDB(B0, 0, 0); PG8_LDB(B1, 0, 1); PG8_SCHED; PG8_LDA(At, 0, 0); PG8_STAGE(PG8_SA(1, 1), a1 + hstep, voffA);
;             PG8_WAIT_V(8); PG8_WAIT_L(0); PG8_BAR; PG8_MMA(0, 0, At, B0); PG8_MMA(0, 1, At, B1); PG8_BAR; PG8_SCHED;
;             PG8_LDA(At, 0, 1); PG8_STAGE(PG8_SB(0, 0), b2, voffB); PG8_STAGE(PG8_SB(0, 1), b2 + hstep, voffB); PG8_STAGE(PG8_SA(0, 0), a2, voffA);
;             PG8_WAIT_V(8); PG8_WAIT_L(0); PG8_BAR; PG8_MMA(1, 0, At, B0); PG8_MMA(1, 1, At, B1); PG8_BAR; PG8_SCHED;
.LBB0_185:
	s_add_u32 s30, s28, 0xfffc0080
	s_addc_u32 s31, s29, -1
	s_add_i32 s55, 0, 0x10000
	s_cmp_eq_u32 s54, 12
	s_cselect_b32 s35, s23, s31
	s_cselect_b32 s34, s33, s30
	v_add_u32_e32 v146, s55, v151
	s_cselect_b32 s31, s21, s53
	s_cselect_b32 s30, s51, s52
	s_add_i32 s58, 0, 0x14000
	s_cmp_lg_u32 s54, 0
	s_cbranch_scc1 .Lodin_nopf
	s_cmp_lt_u32 s39, 0x1000
	s_cbranch_scc0 .Lodin_nopf
	s_lshl_b32 s98, s5, 12
	s_add_u32 s98, s10, s98
	s_addc_u32 s99, s11, 0
	v_lshlrev_b32_e32 v232, 4, v174
	s_add_i32 m0, s39, 0x21000
	s_nop 0
	global_load_lds_dwordx4 v232, s[98:99]
.Lodin_nopf:
	ds_read_b128 v[130:133], v146
	ds_read_b128 v[154:157], v146 offset:1024
	ds_read_b128 v[158:161], v146 offset:2048
	ds_read_b128 v[162:165], v146 offset:3072
	v_add_u32_e32 v146, s58, v151
	ds_read_b128 v[166:169], v146
	ds_read_b128 v[170:173], v146 offset:1024
	ds_read_b128 v[180:183], v146 offset:2048
	ds_read_b128 v[184:187], v146 offset:3072
	v_lshl_add_u64 v[146:147], s[28:29], 0, v[142:143]
	s_add_i32 m0, s40, 0xc000
	ds_read_b128 v[188:191], v153
	ds_read_b128 v[192:195], v153 offset:1024
	ds_read_b128 v[196:199], v153 offset:2048
	ds_read_b128 v[200:203], v153 offset:3072
	ds_read_b128 v[204:207], v153 offset:4096
	ds_read_b128 v[208:211], v153 offset:5120
	ds_read_b128 v[212:215], v153 offset:6144
	ds_read_b128 v[216:219], v153 offset:7168
	global_load_lds_dwordx4 v[146:147], off
	v_lshl_add_u64 v[146:147], s[28:29], 0, v[144:145]
	s_add_i32 m0, s40, 0xe000
	s_nop 0
	global_load_lds_dwordx4 v[146:147], off
	s_waitcnt vmcnt(8)
	s_waitcnt lgkmcnt(0)
	s_barrier
	s_setprio 1
	s_waitcnt lgkmcnt(0)
	v_mfma_f32_16x16x32_bf16 v[70:73], v[130:133], v[188:191], v[70:73]
	v_mfma_f32_16x16x32_bf16 v[66:69], v[158:161], v[188:191], v[66:69]
	v_mfma_f32_16x16x32_bf16 v[62:65], v[130:133], v[196:199], v[62:65]
	v_mfma_f32_16x16x32_bf16 v[58:61], v[158:161], v[196:199], v[58:61]
	v_mfma_f32_16x16x32_bf16 v[54:57], v[130:133], v[204:207], v[54:57]
	v_mfma_f32_16x16x32_bf16 v[50:53], v[158:161], v[204:207], v[50:53]
	v_mfma_f32_16x16x32_bf16 v[46:49], v[130:133], v[212:215], v[46:49]
	v_mfma_f32_16x16x32_bf16 v[42:45], v[158:161], v[212:215], v[42:45]
	v_mfma_f32_16x16x32_bf16 v[70:73], v[154:157], v[192:195], v[70:73]
	v_mfma_f32_16x16x32_bf16 v[66:69], v[162:165], v[192:195], v[66:69]
	v_mfma_f32_16x16x32_bf16 v[62:65], v[154:157], v[200:203], v[62:65]
	v_mfma_f32_16x16x32_bf16 v[58:61], v[162:165], v[200:203], v[58:61]
	v_mfma_f32_16x16x32_bf16 v[54:57], v[154:157], v[208:211], v[54:57]
	v_mfma_f32_16x16x32_bf16 v[50:53], v[162:165], v[208:211], v[50:53]
	v_mfma_f32_16x16x32_bf16 v[46:49], v[154:157], v[216:219], v[46:49]
	v_mfma_f32_16x16x32_bf16 v[42:45], v[162:165], v[216:219], v[42:45]
	s_setprio 0
	s_setprio 1
	v_mfma_f32_16x16x32_bf16 v[126:129], v[166:169], v[188:191], v[126:129]
	v_mfma_f32_16x16x32_bf16 v[122:125], v[180:183], v[188:191], v[122:125]
	v_mfma_f32_16x16x32_bf16 v[118:121], v[166:169], v[196:199], v[118:121]
	v_mfma_f32_16x16x32_bf16 v[114:117], v[180:183], v[196:199], v[114:117]
	v_mfma_f32_16x16x32_bf16 v[110:113], v[166:169], v[204:207], v[110:113]
	v_mfma_f32_16x16x32_bf16 v[106:109], v[180:183], v[204:207], v[106:109]
	v_mfma_f32_16x16x32_bf16 v[102:105], v[166:169], v[212:215], v[102:105]
	v_mfma_f32_16x16x32_bf16 v[98:101], v[180:183], v[212:215], v[98:101]
	v_mfma_f32_16x16x32_bf16 v[126:129], v[170:173], v[192:195], v[126:129]
	v_mfma_f32_16x16x32_bf16 v[122:125], v[184:187], v[192:195], v[122:125]
	v_mfma_f32_16x16x32_bf16 v[118:121], v[170:173], v[200:203], v[118:121]
	v_mfma_f32_16x16x32_bf16 v[114:117], v[184:187], v[200:203], v[114:117]
	v_mfma_f32_16x16x32_bf16 v[110:113], v[170:173], v[208:211], v[110:113]
	v_mfma_f32_16x16x32_bf16 v[106:109], v[184:187], v[208:211], v[106:109]
	v_mfma_f32_16x16x32_bf16 v[102:105], v[170:173], v[216:219], v[102:105]
	v_mfma_f32_16x16x32_bf16 v[98:101], v[184:187], v[216:219], v[98:101]
	s_setprio 0
	s_barrier
	s_add_i32 s55, s55, s39
	v_lshl_add_u64 v[146:147], s[30:31], 0, v[138:139]
	s_mov_b32 m0, s55
	ds_read_b128 v[188:191], v153 offset:16384
	ds_read_b128 v[192:195], v153 offset:17408
	ds_read_b128 v[196:199], v153 offset:18432
	ds_read_b128 v[200:203], v153 offset:19456
	ds_read_b128 v[204:207], v153 offset:20480
	ds_read_b128 v[208:211], v153 offset:21504
	ds_read_b128 v[212:215], v153 offset:22528
	ds_read_b128 v[216:219], v153 offset:23552
	global_load_lds_dwordx4 v[146:147], off
	s_add_i32 m0, s55, 0x2000
	s_add_u32 s56, s30, 0x40000
	v_lshl_add_u64 v[220:221], s[30:31], 0, v[134:135]
	s_addc_u32 s57, s31, 0
	s_add_i32 s55, s58, s39
	global_load_lds_dwordx4 v[220:221], off
	v_lshl_add_u64 v[222:223], s[56:57], 0, v[138:139]
	s_mov_b32 m0, s55
	v_lshl_add_u64 v[228:229], s[34:35], 0, v[136:137]
	global_load_lds_dwordx4 v[222:223], off
	v_lshl_add_u64 v[222:223], s[56:57], 0, v[134:135]
	s_add_i32 m0, s55, 0x2000
	s_nop 0
	global_load_lds_dwordx4 v[222:223], off
	v_lshl_add_u64 v[222:223], s[34:35], 0, v[140:141]
	s_mov_b32 m0, s40
	s_nop 0
	global_load_lds_dwordx4 v[222:223], off
	s_mov_b32 m0, s41
	s_nop 0
	global_load_lds_dwordx4 v[228:229], off
	s_waitcnt vmcnt(8)
	s_waitcnt lgkmcnt(0)
	s_barrier
; #define PG8_STAGE(bufoff, gbase, voff) do { _Pragma("unroll") for (int _i = 0; _i < 2; ++_i) \
;         __builtin_amdgcn_global_load_lds((const unsigned*)((const char*)(gbase) + (voff)[_i]), (PG8_LAS unsigned*)(lds + (bufoff) + ldsw + _i * 8192), 16, 0, 0); } while (0)
; #define PG8_LDA(dst, b, h) do { _Pragma("unroll") for (int m = 0; m < 4; ++m) _Pragma("unroll") for (int k = 0; k < 2; ++k) dst[m][k] = *(const PG8_LAS bf16x8*)(lds + PG8_SA(b, h) + aoff + m * 2048 + k * 1024); } while (0)
; #define PG8_LDB(dst, b, h) do { _Pragma("unroll") for (int n = 0; n < 2; ++n) _Pragma("unroll") for (int k = 0; k < 2; ++k) dst[n][k] = *(const PG8_LAS bf16x8*)(lds + PG8_SB(b, h) + boff + n * 2048 + k * 1024); } while (0)
; #define PG8_MMA(ai, bj, At, Bt) do { __builtin_amdgcn_s_setprio(1); _Pragma("unroll") for (int m = 0; m < 4; ++m) _Pragma("unroll") for (int n = 0; n < 2; ++n) _Pragma("unroll") for (int k = 0; k < 2; ++k) \
;         acc[ai][bj][m][n] = __builtin_amdgcn_mfma_f32_16x16x32_bf16(Bt[n][k], At[m][k], acc[ai][bj][m][n], 0, 0, 0); __builtin_amdgcn_s_setprio(0); } while (0)
; #define PG8_WAIT_V(n) asm volatile("s_waitcnt vmcnt(" #n ")" ::: "memory")
; #define PG8_WAIT_L(n) asm volatile("s_waitcnt lgkmcnt(" #n ")" ::: "memory")
; #define PG8_BAR __builtin_amdgcn_s_barrier()
; #define PG8_SCHED __builtin_amdgcn_sched_barrier(0)
; template <class Epi, class Sched, bool ALIGN_EPI = false, bool SP2 = false>
; __device__ __forceinline__ void gemm_phase(PG8_LAS unsigned char* lds, const Gemm g, const Sched& S, const Epi& E) {
;     ...
;             PG8_WAIT_V(8); PG8_WAIT_L(0); PG8_BAR; PG8_MMA(1, 0, At, B0); PG8_MMA(1, 1, At, B1); PG8_BAR; PG8_SCHED;
;             PG8_LDB(B0, 1, 0); PG8_LDB(B1, 1, 1); PG8_SCHED; PG8_LDA(At, 1, 0); PG8_STAGE(PG8_SA(0, 1), a2 + hstep, voffA);
;             PG8_WAIT_V(8); PG8_WAIT_L(0); PG8_BAR; PG8_MMA(0, 0, At, B0); PG8_MMA(0, 1, At, B1); PG8_BAR; PG8_SCHED;
	s_setprio 1
	s_waitcnt lgkmcnt(0)
	v_mfma_f32_16x16x32_bf16 v[30:33], v[130:133], v[188:191], v[30:33]
	v_mfma_f32_16x16x32_bf16 v[26:29], v[158:161], v[188:191], v[26:29]
	v_mfma_f32_16x16x32_bf16 v[22:25], v[130:133], v[196:199], v[22:25]
	v_mfma_f32_16x16x32_bf16 v[18:21], v[158:161], v[196:199], v[18:21]
	v_mfma_f32_16x16x32_bf16 v[14:17], v[130:133], v[204:207], v[14:17]
	v_mfma_f32_16x16x32_bf16 v[10:13], v[158:161], v[204:207], v[10:13]
	v_mfma_f32_16x16x32_bf16 v[6:9], v[130:133], v[212:215], v[6:9]
	v_mfma_f32_16x16x32_bf16 v[2:5], v[158:161], v[212:215], v[2:5]
	v_mfma_f32_16x16x32_bf16 v[30:33], v[154:157], v[192:195], v[30:33]
	v_mfma_f32_16x16x32_bf16 v[26:29], v[162:165], v[192:195], v[26:29]
	v_mfma_f32_16x16x32_bf16 v[22:25], v[154:157], v[200:203], v[22:25]
	v_mfma_f32_16x16x32_bf16 v[18:21], v[162:165], v[200:203], v[18:21]
	v_mfma_f32_16x16x32_bf16 v[14:17], v[154:157], v[208:211], v[14:17]
	v_mfma_f32_16x16x32_bf16 v[10:13], v[162:165], v[208:211], v[10:13]
	v_mfma_f32_16x16x32_bf16 v[6:9], v[154:157], v[216:219], v[6:9]
	v_mfma_f32_16x16x32_bf16 v[2:5], v[162:165], v[216:219], v[2:5]
	s_setprio 0
	s_setprio 1
	v_mfma_f32_16x16x32_bf16 v[94:97], v[166:169], v[188:191], v[94:97]
	v_mfma_f32_16x16x32_bf16 v[90:93], v[180:183], v[188:191], v[90:93]
	v_mfma_f32_16x16x32_bf16 v[86:89], v[166:169], v[196:199], v[86:89]
	v_mfma_f32_16x16x32_bf16 v[82:85], v[180:183], v[196:199], v[82:85]
	v_mfma_f32_16x16x32_bf16 v[78:81], v[166:169], v[204:207], v[78:81]
	v_mfma_f32_16x16x32_bf16 v[74:77], v[180:183], v[204:207], v[74:77]
	v_mfma_f32_16x16x32_bf16 v[38:41], v[166:169], v[212:215], v[38:41]
	v_mfma_f32_16x16x32_bf16 v[34:37], v[180:183], v[212:215], v[34:37]
	v_mfma_f32_16x16x32_bf16 v[94:97], v[170:173], v[192:195], v[94:97]
	v_mfma_f32_16x16x32_bf16 v[90:93], v[184:187], v[192:195], v[90:93]
	v_mfma_f32_16x16x32_bf16 v[86:89], v[170:173], v[200:203], v[86:89]
	v_mfma_f32_16x16x32_bf16 v[82:85], v[184:187], v[200:203], v[82:85]
	v_mfma_f32_16x16x32_bf16 v[78:81], v[170:173], v[208:211], v[78:81]
	v_mfma_f32_16x16x32_bf16 v[74:77], v[184:187], v[208:211], v[74:77]
	v_mfma_f32_16x16x32_bf16 v[38:41], v[170:173], v[216:219], v[38:41]
	v_mfma_f32_16x16x32_bf16 v[34:37], v[184:187], v[216:219], v[34:37]
	s_setprio 0
	s_barrier
	s_add_i32 s55, 0, 0x18000
	v_add_u32_e32 v148, s55, v151
	s_add_i32 s56, 0, 0x1c000
	ds_read_b128 v[130:133], v148
	ds_read_b128 v[154:157], v148 offset:1024
	ds_read_b128 v[158:161], v148 offset:2048
	ds_read_b128 v[162:165], v148 offset:3072
	v_add_u32_e32 v148, s56, v151
	ds_read_b128 v[166:169], v148
	ds_read_b128 v[170:173], v148 offset:1024
	ds_read_b128 v[180:183], v148 offset:2048
	ds_read_b128 v[184:187], v148 offset:3072
	s_add_u32 s34, s34, 0x40000
	s_addc_u32 s35, s35, 0
	s_mov_b32 m0, s42
	v_lshl_add_u64 v[230:231], s[34:35], 0, v[140:141]
	ds_read_b128 v[188:191], v153 offset:32768
	ds_read_b128 v[192:195], v153 offset:33792
	ds_read_b128 v[196:199], v153 offset:34816
	ds_read_b128 v[200:203], v153 offset:35840
	ds_read_b128 v[204:207], v153 offset:36864
	ds_read_b128 v[208:211], v153 offset:37888
	ds_read_b128 v[212:215], v153 offset:38912
	ds_read_b128 v[216:219], v153 offset:39936
	global_load_lds_dwordx4 v[230:231], off
	v_lshl_add_u64 v[230:231], s[34:35], 0, v[136:137]
	s_mov_b32 m0, s43
	s_nop 0
	global_load_lds_dwordx4 v[230:231], off
	s_waitcnt vmcnt(8)
	s_waitcnt lgkmcnt(0)
	s_barrier
	s_setprio 1
	s_waitcnt lgkmcnt(0)
	v_mfma_f32_16x16x32_bf16 v[70:73], v[130:133], v[188:191], v[70:73]
	v_mfma_f32_16x16x32_bf16 v[66:69], v[158:161], v[188:191], v[66:69]
	v_mfma_f32_16x16x32_bf16 v[62:65], v[130:133], v[196:199], v[62:65]
	v_mfma_f32_16x16x32_bf16 v[58:61], v[158:161], v[196:199], v[58:61]
	v_mfma_f32_16x16x32_bf16 v[54:57], v[130:133], v[204:207], v[54:57]
	v_mfma_f32_16x16x32_bf16 v[50:53], v[158:161], v[204:207], v[50:53]
	v_mfma_f32_16x16x32_bf16 v[46:49], v[130:133], v[212:215], v[46:49]
	v_mfma_f32_16x16x32_bf16 v[42:45], v[158:161], v[212:215], v[42:45]
	v_mfma_f32_16x16x32_bf16 v[70:73], v[154:157], v[192:195], v[70:73]
	v_mfma_f32_16x16x32_bf16 v[66:69], v[162:165], v[192:195], v[66:69]
	v_mfma_f32_16x16x32_bf16 v[62:65], v[154:157], v[200:203], v[62:65]
	v_mfma_f32_16x16x32_bf16 v[58:61], v[162:165], v[200:203], v[58:61]
	v_mfma_f32_16x16x32_bf16 v[54:57], v[154:157], v[208:211], v[54:57]
	v_mfma_f32_16x16x32_bf16 v[50:53], v[162:165], v[208:211], v[50:53]
	v_mfma_f32_16x16x32_bf16 v[46:49], v[154:157], v[216:219], v[46:49]
	v_mfma_f32_16x16x32_bf16 v[42:45], v[162:165], v[216:219], v[42:45]
	s_setprio 0
	s_setprio 1
	v_mfma_f32_16x16x32_bf16 v[126:129], v[166:169], v[188:191], v[126:129]
	v_mfma_f32_16x16x32_bf16 v[122:125], v[180:183], v[188:191], v[122:125]
	v_mfma_f32_16x16x32_bf16 v[118:121], v[166:169], v[196:199], v[118:121]
	v_mfma_f32_16x16x32_bf16 v[114:117], v[180:183], v[196:199], v[114:117]
	v_mfma_f32_16x16x32_bf16 v[110:113], v[166:169], v[204:207], v[110:113]
	v_mfma_f32_16x16x32_bf16 v[106:109], v[180:183], v[204:207], v[106:109]
	v_mfma_f32_16x16x32_bf16 v[102:105], v[166:169], v[212:215], v[102:105]
	v_mfma_f32_16x16x32_bf16 v[98:101], v[180:183], v[212:215], v[98:101]
	v_mfma_f32_16x16x32_bf16 v[126:129], v[170:173], v[192:195], v[126:129]
	v_mfma_f32_16x16x32_bf16 v[122:125], v[184:187], v[192:195], v[122:125]
	v_mfma_f32_16x16x32_bf16 v[118:121], v[170:173], v[200:203], v[118:121]
	v_mfma_f32_16x16x32_bf16 v[114:117], v[184:187], v[200:203], v[114:117]
	v_mfma_f32_16x16x32_bf16 v[110:113], v[170:173], v[208:211], v[110:113]
	v_mfma_f32_16x16x32_bf16 v[106:109], v[184:187], v[208:211], v[106:109]
	v_mfma_f32_16x16x32_bf16 v[102:105], v[170:173], v[216:219], v[102:105]
	v_mfma_f32_16x16x32_bf16 v[98:101], v[184:187], v[216:219], v[98:101]
	s_setprio 0
	s_barrier
; #define PG8_STAGE(bufoff, gbase, voff) do { _Pragma("unroll") for (int _i = 0; _i < 2; ++_i) \
;         __builtin_amdgcn_global_load_lds((const unsigned*)((const char*)(gbase) + (voff)[_i]), (PG8_LAS unsigned*)(lds + (bufoff) + ldsw + _i * 8192), 16, 0, 0); } while (0)
; #define PG8_LDA(dst, b, h) do { _Pragma("unroll") for (int m = 0; m < 4; ++m) _Pragma("unroll") for (int k = 0; k < 2; ++k) dst[m][k] = *(const PG8_LAS bf16x8*)(lds + PG8_SA(b, h) + aoff + m * 2048 + k * 1024); } while (0)
; #define PG8_MMA(ai, bj, At, Bt) do { __builtin_amdgcn_s_setprio(1); _Pragma("unroll") for (int m = 0; m < 4; ++m) _Pragma("unroll") for (int n = 0; n < 2; ++n) _Pragma("unroll") for (int k = 0; k < 2; ++k) \
;         acc[ai][bj][m][n] = __builtin_amdgcn_mfma_f32_16x16x32_bf16(Bt[n][k], At[m][k], acc[ai][bj][m][n], 0, 0, 0); __builtin_amdgcn_s_setprio(0); } while (0)
; #define PG8_WAIT_V(n) asm volatile("s_waitcnt vmcnt(" #n ")" ::: "memory")
; #define PG8_WAIT_L(n) asm volatile("s_waitcnt lgkmcnt(" #n ")" ::: "memory")
; #define PG8_BAR __builtin_amdgcn_s_barrier()
; #define PG8_SCHED __builtin_amdgcn_sched_barrier(0)
;     __device__ __forceinline__ void operator()(const f32x4 (&acc)[2][2][4][2], const Unit& u, int wr, int wc, int fr, int fq) const {
;     ...
;         int colt = u.pn * BM; bf16_t* base = O; float sc = 1.f;
;         if (split_cols) { const int t = colt / split_cols; base += (size_t)t * split_stride; colt -= t * split_cols; if (t == 0) sc = scale0; }
;         const int col0 = colt + wc * 32 + 8 * fq;
;         float rsv[2][4];
; #pragma unroll
;         for (int ai = 0; ai < 2; ++ai)
; #pragma unroll
;             for (int m = 0; m < 4; ++m) rsv[ai][m] = row_rstd(ssq, row0 + ai * HALF + m * 16 + row_off) * sc;
; template <class Epi, class Sched, bool ALIGN_EPI = false, bool SP2 = false>
; __device__ __forceinline__ void gemm_phase(PG8_LAS unsigned char* lds, const Gemm g, const Sched& S, const Epi& E) {
;     ...
;             PG8_LDA(At, 1, 1); PG8_STAGE(PG8_SB(1, 0), b3, voffB); PG8_STAGE(PG8_SB(1, 1), b3 + hstep, voffB); PG8_STAGE(PG8_SA(1, 0), a3, voffA);
;             PG8_WAIT_V(8); PG8_WAIT_L(0); PG8_BAR; PG8_MMA(1, 0, At, B0); PG8_MMA(1, 1, At, B1); PG8_BAR; PG8_SCHED;
	s_add_i32 s34, s55, s39
	v_lshl_add_u64 v[146:147], v[146:147], 0, s[96:97]
	s_mov_b32 m0, s34
	ds_read_b128 v[188:191], v153 offset:49152
	ds_read_b128 v[192:195], v153 offset:50176
	ds_read_b128 v[196:199], v153 offset:51200
	ds_read_b128 v[200:203], v153 offset:52224
	ds_read_b128 v[204:207], v153 offset:53248
	ds_read_b128 v[208:211], v153 offset:54272
	ds_read_b128 v[212:215], v153 offset:55296
	ds_read_b128 v[216:219], v153 offset:56320
	global_load_lds_dwordx4 v[146:147], off
	s_add_i32 m0, s34, 0x2000
	s_add_u32 s30, s30, 0x40080
	v_lshl_add_u64 v[146:147], v[220:221], 0, s[96:97]
	s_addc_u32 s31, s31, 0
	s_add_i32 s34, s56, s39
	global_load_lds_dwordx4 v[146:147], off
	v_lshl_add_u64 v[146:147], s[30:31], 0, v[138:139]
	s_mov_b32 m0, s34
	s_nop 0
	global_load_lds_dwordx4 v[146:147], off
	v_lshl_add_u64 v[146:147], s[30:31], 0, v[134:135]
	s_add_i32 m0, s34, 0x2000
	s_nop 0
	global_load_lds_dwordx4 v[146:147], off
	v_lshl_add_u64 v[146:147], v[222:223], 0, s[96:97]
	s_mov_b32 m0, s48
	s_nop 0
	global_load_lds_dwordx4 v[146:147], off
	v_lshl_add_u64 v[146:147], v[228:229], 0, s[96:97]
	s_mov_b32 m0, s49
	s_nop 0
	global_load_lds_dwordx4 v[146:147], off
	s_waitcnt vmcnt(8)
	s_waitcnt lgkmcnt(0)
	s_barrier
	s_setprio 1
	s_waitcnt lgkmcnt(0)
	v_mfma_f32_16x16x32_bf16 v[30:33], v[130:133], v[188:191], v[30:33]
	v_mfma_f32_16x16x32_bf16 v[26:29], v[158:161], v[188:191], v[26:29]
	v_mfma_f32_16x16x32_bf16 v[22:25], v[130:133], v[196:199], v[22:25]
	v_mfma_f32_16x16x32_bf16 v[18:21], v[158:161], v[196:199], v[18:21]
	v_mfma_f32_16x16x32_bf16 v[14:17], v[130:133], v[204:207], v[14:17]
	v_mfma_f32_16x16x32_bf16 v[10:13], v[158:161], v[204:207], v[10:13]
	v_mfma_f32_16x16x32_bf16 v[6:9], v[130:133], v[212:215], v[6:9]
	v_mfma_f32_16x16x32_bf16 v[2:5], v[158:161], v[212:215], v[2:5]
	v_mfma_f32_16x16x32_bf16 v[30:33], v[154:157], v[192:195], v[30:33]
	v_mfma_f32_16x16x32_bf16 v[26:29], v[162:165], v[192:195], v[26:29]
	v_mfma_f32_16x16x32_bf16 v[22:25], v[154:157], v[200:203], v[22:25]
	v_mfma_f32_16x16x32_bf16 v[18:21], v[162:165], v[200:203], v[18:21]
	v_mfma_f32_16x16x32_bf16 v[14:17], v[154:157], v[208:211], v[14:17]
	v_mfma_f32_16x16x32_bf16 v[10:13], v[162:165], v[208:211], v[10:13]
	v_mfma_f32_16x16x32_bf16 v[6:9], v[154:157], v[216:219], v[6:9]
	v_mfma_f32_16x16x32_bf16 v[2:5], v[162:165], v[216:219], v[2:5]
	s_setprio 0
	s_setprio 1
	v_mfma_f32_16x16x32_bf16 v[94:97], v[166:169], v[188:191], v[94:97]
	v_mfma_f32_16x16x32_bf16 v[90:93], v[180:183], v[188:191], v[90:93]
	v_mfma_f32_16x16x32_bf16 v[86:89], v[166:169], v[196:199], v[86:89]
	v_mfma_f32_16x16x32_bf16 v[82:85], v[180:183], v[196:199], v[82:85]
	v_mfma_f32_16x16x32_bf16 v[78:81], v[166:169], v[204:207], v[78:81]
	v_mfma_f32_16x16x32_bf16 v[74:77], v[180:183], v[204:207], v[74:77]
	v_mfma_f32_16x16x32_bf16 v[38:41], v[166:169], v[212:215], v[38:41]
	v_mfma_f32_16x16x32_bf16 v[34:37], v[180:183], v[212:215], v[34:37]
	v_mfma_f32_16x16x32_bf16 v[94:97], v[170:173], v[192:195], v[94:97]
	v_mfma_f32_16x16x32_bf16 v[90:93], v[184:187], v[192:195], v[90:93]
	v_mfma_f32_16x16x32_bf16 v[86:89], v[170:173], v[200:203], v[86:89]
	v_mfma_f32_16x16x32_bf16 v[82:85], v[184:187], v[200:203], v[82:85]
	v_mfma_f32_16x16x32_bf16 v[78:81], v[170:173], v[208:211], v[78:81]
	v_mfma_f32_16x16x32_bf16 v[74:77], v[184:187], v[208:211], v[74:77]
	v_mfma_f32_16x16x32_bf16 v[38:41], v[170:173], v[216:219], v[38:41]
	v_mfma_f32_16x16x32_bf16 v[34:37], v[184:187], v[216:219], v[34:37]
	s_setprio 0
	s_barrier
	s_add_i32 s54, s54, 2
	s_add_u32 s28, s28, 0x100
	s_addc_u32 s29, s29, 0
	s_add_u32 s52, s52, 0x100
	s_addc_u32 s53, s53, 0
	s_cmp_gt_u32 s54, 13
	s_cbranch_scc0 .LBB0_185
	s_and_b64 vcc, exec, s[16:17]
	s_cbranch_vccz .LBB0_188
	s_barrier
.LBB0_188:
	v_add_u32_e32 v233, s46, v1
	v_lshlrev_b32_e32 v233, 4, v233
	v_add_u32_e32 v233, 0x21000, v233
	s_lshl_b32 s5, s5, 8
	v_mov_b32_e32 v155, v149
	v_mov_b32_e32 v130, v1
	s_add_i32 s5, s5, s46
	s_cmp_lg_u32 s4, 12
	v_add_u32_e32 v146, s5, v130
	s_mov_b64 s[28:29], -1
	s_cbranch_scc0 .LBB0_191
	s_ashr_i32 s21, s4, 31
	s_lshr_b32 s21, s21, 30
	s_add_i32 s21, s4, s21
	s_ashr_i32 s30, s21, 2
	s_ashr_i32 s31, s30, 31
	s_lshl_b32 s5, s4, 8
	s_lshl_b64 s[28:29], s[30:31], 26
	s_add_u32 s28, s44, s28
	s_addc_u32 s29, s45, s29
	s_add_i32 s4, s4, 3
	s_cmp_lt_u32 s4, 7
	s_cselect_b64 vcc, -1, 0
	v_mov_b32_e32 v130, 0x3e38aa3b
	v_ashrrev_i32_e32 v147, 31, v146
	v_cndmask_b32_e32 v157, 1.0, v130, vcc
	ds_read_b128 v[130:133], v233
	v_add_u32_e32 v180, 16, v146
	v_ashrrev_i32_e32 v181, 31, v180
	v_add_u32_e32 v172, 32, v146
	v_ashrrev_i32_e32 v173, 31, v172
	v_add_u32_e32 v170, 48, v146
	v_ashrrev_i32_e32 v171, 31, v170
	v_add_u32_e32 v168, 0x80, v146
	v_ashrrev_i32_e32 v169, 31, v168
	v_add_u32_e32 v166, 0x90, v146
	v_ashrrev_i32_e32 v167, 31, v166
	v_add_u32_e32 v164, 0xa0, v146
	v_ashrrev_i32_e32 v165, 31, v164
	s_or_b32 s4, s5, s47
	s_lshl_b32 s5, s30, 10
	s_sub_i32 s4, s4, s5
	s_waitcnt lgkmcnt(0)
	v_mov_b32_e32 v158, v131
	v_mov_b32_e32 v159, v132
	v_mov_b32_e32 v131, v133
	v_pk_add_f32 v[130:131], v[158:159], v[130:131]
	s_nop 0
	v_add_f32_e32 v130, v130, v131
	v_fmamk_f32 v130, v130, 0x3a800000, v175
	v_rsq_f32_e32 v130, v130
	s_nop 0
	v_mul_f32_e32 v160, v157, v130
	ds_read_b128 v[130:133], v233 offset:256
	v_pk_mul_f32 v[184:185], v[72:73], v[160:161] op_sel_hi:[1,0]
	v_pk_mul_f32 v[188:189], v[68:69], v[160:161] op_sel_hi:[1,0]
	v_pk_mul_f32 v[190:191], v[66:67], v[160:161] op_sel_hi:[1,0]
	v_pk_mul_f32 v[128:129], v[128:129], v[160:161] op_sel_hi:[1,0]
	v_pk_mul_f32 v[126:127], v[126:127], v[160:161] op_sel_hi:[1,0]
	s_waitcnt lgkmcnt(0)
; __device__ __forceinline__ unsigned cvt_pk_bf16(float lo, float hi) { unsigned r; asm volatile("v_cvt_pk_bf16_f32 %0, %1, %2" : "=v"(r) : "v"(lo), "v"(hi)); return r; }
;     __device__ __forceinline__ void operator()(const f32x4 (&acc)[2][2][4][2], const Unit& u, int wr, int wc, int fr, int fq) const {
;     ...
;         float rsv[2][4];
; #pragma unroll
;         for (int ai = 0; ai < 2; ++ai)
; #pragma unroll
;             for (int m = 0; m < 4; ++m) rsv[ai][m] = row_rstd(ssq, row0 + ai * HALF + m * 16 + row_off) * sc;
; #pragma unroll
;         for (int ai = 0; ai < 2; ++ai)
; #pragma unroll
;             for (int m = 0; m < 4; ++m) { const int row = row0 + ai * HALF + m * 16; const float rs = rsv[ai][m]; bf16_t* rowp = base + (size_t)row * ldc + col0;
; #pragma unroll
;                 for (int bj = 0; bj < 2; ++bj) { const f32x4 v0 = acc[ai][bj][m][0] * rs, v1 = acc[ai][bj][m][1] * rs;
;                     u32x4 w; w.x = cvt_pk_bf16(v0[0], v0[1]); w.y = cvt_pk_bf16(v0[2], v0[3]); w.z = cvt_pk_bf16(v1[0], v1[1]); w.w = cvt_pk_bf16(v1[2], v1[3]);
;                     *(u32x4*)(rowp + bj * HALF) = w; } asm volatile("" ::: "memory"); }
	v_mov_b32_e32 v158, v131
	v_mov_b32_e32 v159, v132
	v_mov_b32_e32 v131, v133
	v_pk_add_f32 v[130:131], v[158:159], v[130:131]
	s_nop 0
	v_add_f32_e32 v130, v130, v131
	v_fmamk_f32 v130, v130, 0x3a800000, v175
	v_rsq_f32_e32 v130, v130
	s_nop 0
	v_mul_f32_e32 v162, v157, v130
	ds_read_b128 v[130:133], v233 offset:512
	v_pk_mul_f32 v[120:121], v[120:121], v[162:163] op_sel_hi:[1,0]
	v_pk_mul_f32 v[118:119], v[118:119], v[162:163] op_sel_hi:[1,0]
	s_waitcnt lgkmcnt(0)
	v_mov_b32_e32 v158, v131
	v_mov_b32_e32 v159, v132
	v_mov_b32_e32 v131, v133
	v_pk_add_f32 v[130:131], v[158:159], v[130:131]
	s_nop 0
	v_add_f32_e32 v130, v130, v131
	v_fmamk_f32 v130, v130, 0x3a800000, v175
	v_rsq_f32_e32 v130, v130
	s_nop 0
	v_mul_f32_e32 v154, v157, v130
	ds_read_b128 v[130:133], v233 offset:768
	v_pk_mul_f32 v[112:113], v[112:113], v[154:155] op_sel_hi:[1,0]
	v_pk_mul_f32 v[110:111], v[110:111], v[154:155] op_sel_hi:[1,0]
	s_waitcnt lgkmcnt(0)
	v_mov_b32_e32 v158, v131
	v_mov_b32_e32 v159, v132
	v_mov_b32_e32 v131, v133
	v_pk_add_f32 v[130:131], v[158:159], v[130:131]
	s_nop 0
	v_add_f32_e32 v130, v130, v131
	v_fmamk_f32 v130, v130, 0x3a800000, v175
	v_rsq_f32_e32 v130, v130
	s_nop 0
	v_mul_f32_e32 v156, v157, v130
	ds_read_b128 v[130:133], v233 offset:2048
	v_pk_mul_f32 v[104:105], v[104:105], v[156:157] op_sel_hi:[1,0]
	v_pk_mul_f32 v[102:103], v[102:103], v[156:157] op_sel_hi:[1,0]
	s_waitcnt lgkmcnt(0)
	v_mov_b32_e32 v158, v131
	v_mov_b32_e32 v159, v132
	v_mov_b32_e32 v131, v133
	v_pk_add_f32 v[130:131], v[158:159], v[130:131]
	s_nop 0
	v_add_f32_e32 v130, v130, v131
	v_fmamk_f32 v130, v130, 0x3a800000, v175
	v_rsq_f32_e32 v130, v130
	s_nop 0
	v_mul_f32_e32 v152, v157, v130
	ds_read_b128 v[130:133], v233 offset:2304
	v_pk_mul_f32 v[96:97], v[96:97], v[152:153] op_sel_hi:[1,0]
	v_pk_mul_f32 v[94:95], v[94:95], v[152:153] op_sel_hi:[1,0]
	s_waitcnt lgkmcnt(0)
	v_mov_b32_e32 v158, v131
	v_mov_b32_e32 v159, v132
	v_mov_b32_e32 v131, v133
	v_pk_add_f32 v[130:131], v[158:159], v[130:131]
	s_nop 0
	v_add_f32_e32 v130, v130, v131
	v_fmamk_f32 v130, v130, 0x3a800000, v175
	v_rsq_f32_e32 v130, v130
	s_nop 0
	v_mul_f32_e32 v150, v157, v130
	ds_read_b128 v[130:133], v233 offset:2560
	v_pk_mul_f32 v[88:89], v[88:89], v[150:151] op_sel_hi:[1,0]
	v_pk_mul_f32 v[86:87], v[86:87], v[150:151] op_sel_hi:[1,0]
	s_waitcnt lgkmcnt(0)
	v_mov_b32_e32 v158, v131
	v_mov_b32_e32 v159, v132
	v_mov_b32_e32 v131, v133
	v_pk_add_f32 v[130:131], v[158:159], v[130:131]
	v_add_u32_e32 v158, 0xb0, v146
	v_add_f32_e32 v130, v130, v131
	v_fmamk_f32 v130, v130, 0x3a800000, v175
	v_rsq_f32_e32 v130, v130
	v_ashrrev_i32_e32 v159, 31, v158
	v_mul_f32_e32 v148, v157, v130
	ds_read_b128 v[130:133], v233 offset:2816
	v_pk_mul_f32 v[80:81], v[80:81], v[148:149] op_sel_hi:[1,0]
	v_pk_mul_f32 v[78:79], v[78:79], v[148:149] op_sel_hi:[1,0]
	s_waitcnt lgkmcnt(0)
	v_mov_b32_e32 v183, v132
	v_lshl_add_u32 v132, v155, 3, s4
	v_mov_b32_e32 v182, v131
	v_mov_b32_e32 v131, v133
	v_ashrrev_i32_e32 v133, 31, v132
	v_pk_add_f32 v[130:131], v[182:183], v[130:131]
	v_lshl_add_u64 v[132:133], v[132:133], 1, s[28:29]
	v_lshlrev_b64 v[182:183], 11, v[146:147]
	v_lshl_add_u64 v[186:187], v[132:133], 0, v[182:183]
	v_pk_mul_f32 v[182:183], v[70:71], v[160:161] op_sel_hi:[1,0]
	v_add_f32_e32 v130, v130, v131
	v_cvt_pk_bf16_f32 v182, v182, v183
	v_cvt_pk_bf16_f32 v183, v184, v185
	v_cvt_pk_bf16_f32 v184, v190, v191
	v_cvt_pk_bf16_f32 v185, v188, v189
	global_store_dwordx4 v[186:187], v[182:185], off
	v_fmamk_f32 v130, v130, 0x3a800000, v175
	v_rsq_f32_e32 v130, v130
	v_pk_mul_f32 v[182:183], v[124:125], v[160:161] op_sel_hi:[1,0]
	v_pk_mul_f32 v[124:125], v[122:123], v[160:161] op_sel_hi:[1,0]
	v_cvt_pk_bf16_f32 v122, v126, v127
	v_cvt_pk_bf16_f32 v123, v128, v129
	v_pk_mul_f32 v[128:129], v[60:61], v[162:163] op_sel_hi:[1,0]
	v_cvt_pk_bf16_f32 v124, v124, v125
	v_cvt_pk_bf16_f32 v125, v182, v183
	global_store_dwordx4 v[186:187], v[122:125], off offset:256
	v_pk_mul_f32 v[160:161], v[58:59], v[162:163] op_sel_hi:[1,0]
	v_mul_f32_e32 v130, v157, v130
	v_lshlrev_b64 v[122:123], 11, v[180:181]
	v_lshl_add_u64 v[126:127], v[132:133], 0, v[122:123]
	v_pk_mul_f32 v[122:123], v[62:63], v[162:163] op_sel_hi:[1,0]
	v_pk_mul_f32 v[124:125], v[64:65], v[162:163] op_sel_hi:[1,0]
	v_cvt_pk_bf16_f32 v122, v122, v123
	v_pk_mul_f32 v[40:41], v[40:41], v[130:131] op_sel_hi:[1,0]
	v_cvt_pk_bf16_f32 v123, v124, v125
	v_cvt_pk_bf16_f32 v124, v160, v161
	v_cvt_pk_bf16_f32 v125, v128, v129
	global_store_dwordx4 v[126:127], v[122:125], off
	v_pk_mul_f32 v[38:39], v[38:39], v[130:131] op_sel_hi:[1,0]
	s_nop 0
	v_pk_mul_f32 v[122:123], v[116:117], v[162:163] op_sel_hi:[1,0]
	v_pk_mul_f32 v[116:117], v[114:115], v[162:163] op_sel_hi:[1,0]
	v_cvt_pk_bf16_f32 v114, v118, v119
	v_cvt_pk_bf16_f32 v115, v120, v121
	v_pk_mul_f32 v[120:121], v[52:53], v[154:155] op_sel_hi:[1,0]
	v_cvt_pk_bf16_f32 v116, v116, v117
	v_cvt_pk_bf16_f32 v117, v122, v123
	global_store_dwordx4 v[126:127], v[114:117], off offset:256
	v_pk_mul_f32 v[122:123], v[50:51], v[154:155] op_sel_hi:[1,0]
	s_nop 0
	v_lshlrev_b64 v[114:115], 11, v[172:173]
; __device__ __forceinline__ unsigned cvt_pk_bf16(float lo, float hi) { unsigned r; asm volatile("v_cvt_pk_bf16_f32 %0, %1, %2" : "=v"(r) : "v"(lo), "v"(hi)); return r; }
;     __device__ __forceinline__ void operator()(const f32x4 (&acc)[2][2][4][2], const Unit& u, int wr, int wc, int fr, int fq) const {
;     ...
; #pragma unroll
;         for (int ai = 0; ai < 2; ++ai)
; #pragma unroll
;             for (int m = 0; m < 4; ++m) { const int row = row0 + ai * HALF + m * 16; const float rs = rsv[ai][m]; bf16_t* rowp = base + (size_t)row * ldc + col0;
; #pragma unroll
;                 for (int bj = 0; bj < 2; ++bj) { const f32x4 v0 = acc[ai][bj][m][0] * rs, v1 = acc[ai][bj][m][1] * rs;
;                     u32x4 w; w.x = cvt_pk_bf16(v0[0], v0[1]); w.y = cvt_pk_bf16(v0[2], v0[3]); w.z = cvt_pk_bf16(v1[0], v1[1]); w.w = cvt_pk_bf16(v1[2], v1[3]);
;                     *(u32x4*)(rowp + bj * HALF) = w; } asm volatile("" ::: "memory"); }
	v_lshl_add_u64 v[118:119], v[132:133], 0, v[114:115]
	v_pk_mul_f32 v[114:115], v[54:55], v[154:155] op_sel_hi:[1,0]
	v_pk_mul_f32 v[116:117], v[56:57], v[154:155] op_sel_hi:[1,0]
	v_cvt_pk_bf16_f32 v114, v114, v115
	s_nop 0
	v_cvt_pk_bf16_f32 v115, v116, v117
	v_cvt_pk_bf16_f32 v116, v122, v123
	v_cvt_pk_bf16_f32 v117, v120, v121
	global_store_dwordx4 v[118:119], v[114:117], off
	s_nop 1
	v_pk_mul_f32 v[114:115], v[108:109], v[154:155] op_sel_hi:[1,0]
	v_pk_mul_f32 v[108:109], v[106:107], v[154:155] op_sel_hi:[1,0]
	v_cvt_pk_bf16_f32 v106, v110, v111
	v_cvt_pk_bf16_f32 v107, v112, v113
	v_pk_mul_f32 v[112:113], v[44:45], v[156:157] op_sel_hi:[1,0]
	v_cvt_pk_bf16_f32 v108, v108, v109
	v_cvt_pk_bf16_f32 v109, v114, v115
	global_store_dwordx4 v[118:119], v[106:109], off offset:256
	v_pk_mul_f32 v[114:115], v[42:43], v[156:157] op_sel_hi:[1,0]
	s_nop 0
	v_lshlrev_b64 v[106:107], 11, v[170:171]
	v_lshl_add_u64 v[110:111], v[132:133], 0, v[106:107]
	v_pk_mul_f32 v[106:107], v[46:47], v[156:157] op_sel_hi:[1,0]
	v_pk_mul_f32 v[108:109], v[48:49], v[156:157] op_sel_hi:[1,0]
	v_cvt_pk_bf16_f32 v106, v106, v107
	s_nop 0
	v_cvt_pk_bf16_f32 v107, v108, v109
	v_cvt_pk_bf16_f32 v108, v114, v115
	v_cvt_pk_bf16_f32 v109, v112, v113
	global_store_dwordx4 v[110:111], v[106:109], off
	s_nop 1
	v_pk_mul_f32 v[106:107], v[100:101], v[156:157] op_sel_hi:[1,0]
	v_pk_mul_f32 v[100:101], v[98:99], v[156:157] op_sel_hi:[1,0]
	v_cvt_pk_bf16_f32 v98, v102, v103
	v_cvt_pk_bf16_f32 v99, v104, v105
	v_pk_mul_f32 v[104:105], v[28:29], v[152:153] op_sel_hi:[1,0]
	v_cvt_pk_bf16_f32 v100, v100, v101
	v_cvt_pk_bf16_f32 v101, v106, v107
	global_store_dwordx4 v[110:111], v[98:101], off offset:256
	v_pk_mul_f32 v[106:107], v[26:27], v[152:153] op_sel_hi:[1,0]
	s_nop 0
	v_lshlrev_b64 v[98:99], 11, v[168:169]
	v_lshl_add_u64 v[102:103], v[132:133], 0, v[98:99]
	v_pk_mul_f32 v[98:99], v[30:31], v[152:153] op_sel_hi:[1,0]
	v_pk_mul_f32 v[100:101], v[32:33], v[152:153] op_sel_hi:[1,0]
	v_cvt_pk_bf16_f32 v98, v98, v99
	s_nop 0
	v_cvt_pk_bf16_f32 v99, v100, v101
	v_cvt_pk_bf16_f32 v100, v106, v107
	v_cvt_pk_bf16_f32 v101, v104, v105
	global_store_dwordx4 v[102:103], v[98:101], off
	s_nop 1
	v_pk_mul_f32 v[98:99], v[92:93], v[152:153] op_sel_hi:[1,0]
	v_pk_mul_f32 v[92:93], v[90:91], v[152:153] op_sel_hi:[1,0]
	v_cvt_pk_bf16_f32 v90, v94, v95
	v_cvt_pk_bf16_f32 v91, v96, v97
	v_pk_mul_f32 v[96:97], v[20:21], v[150:151] op_sel_hi:[1,0]
	v_cvt_pk_bf16_f32 v92, v92, v93
	v_cvt_pk_bf16_f32 v93, v98, v99
	global_store_dwordx4 v[102:103], v[90:93], off offset:256
	v_pk_mul_f32 v[98:99], v[18:19], v[150:151] op_sel_hi:[1,0]
	s_nop 0
	v_lshlrev_b64 v[90:91], 11, v[166:167]
	v_lshl_add_u64 v[94:95], v[132:133], 0, v[90:91]
	v_pk_mul_f32 v[90:91], v[22:23], v[150:151] op_sel_hi:[1,0]
	v_pk_mul_f32 v[92:93], v[24:25], v[150:151] op_sel_hi:[1,0]
	v_cvt_pk_bf16_f32 v90, v90, v91
	s_nop 0
	v_cvt_pk_bf16_f32 v91, v92, v93
	v_cvt_pk_bf16_f32 v92, v98, v99
	v_cvt_pk_bf16_f32 v93, v96, v97
	global_store_dwordx4 v[94:95], v[90:93], off
	s_nop 1
	v_pk_mul_f32 v[90:91], v[84:85], v[150:151] op_sel_hi:[1,0]
	v_pk_mul_f32 v[84:85], v[82:83], v[150:151] op_sel_hi:[1,0]
	v_cvt_pk_bf16_f32 v82, v86, v87
	v_cvt_pk_bf16_f32 v83, v88, v89
	v_pk_mul_f32 v[88:89], v[12:13], v[148:149] op_sel_hi:[1,0]
	v_cvt_pk_bf16_f32 v84, v84, v85
	v_cvt_pk_bf16_f32 v85, v90, v91
	global_store_dwordx4 v[94:95], v[82:85], off offset:256
	v_pk_mul_f32 v[90:91], v[10:11], v[148:149] op_sel_hi:[1,0]
	s_nop 0
	v_lshlrev_b64 v[82:83], 11, v[164:165]
	v_lshl_add_u64 v[86:87], v[132:133], 0, v[82:83]
	v_pk_mul_f32 v[82:83], v[14:15], v[148:149] op_sel_hi:[1,0]
	v_pk_mul_f32 v[84:85], v[16:17], v[148:149] op_sel_hi:[1,0]
	v_cvt_pk_bf16_f32 v82, v82, v83
	s_nop 0
	v_cvt_pk_bf16_f32 v83, v84, v85
	v_cvt_pk_bf16_f32 v84, v90, v91
	v_cvt_pk_bf16_f32 v85, v88, v89
	global_store_dwordx4 v[86:87], v[82:85], off
	s_nop 1
	v_pk_mul_f32 v[82:83], v[76:77], v[148:149] op_sel_hi:[1,0]
	v_pk_mul_f32 v[76:77], v[74:75], v[148:149] op_sel_hi:[1,0]
	v_cvt_pk_bf16_f32 v74, v78, v79
	v_cvt_pk_bf16_f32 v75, v80, v81
	v_pk_mul_f32 v[80:81], v[4:5], v[130:131] op_sel_hi:[1,0]
	v_cvt_pk_bf16_f32 v76, v76, v77
	v_cvt_pk_bf16_f32 v77, v82, v83
	global_store_dwordx4 v[86:87], v[74:77], off offset:256
	v_pk_mul_f32 v[82:83], v[2:3], v[130:131] op_sel_hi:[1,0]
	s_nop 0
	v_lshlrev_b64 v[74:75], 11, v[158:159]
	v_lshl_add_u64 v[78:79], v[132:133], 0, v[74:75]
	v_pk_mul_f32 v[74:75], v[6:7], v[130:131] op_sel_hi:[1,0]
	v_pk_mul_f32 v[76:77], v[8:9], v[130:131] op_sel_hi:[1,0]
	v_cvt_pk_bf16_f32 v74, v74, v75
	s_nop 0
	v_cvt_pk_bf16_f32 v75, v76, v77
	v_cvt_pk_bf16_f32 v76, v82, v83
	v_cvt_pk_bf16_f32 v77, v80, v81
	global_store_dwordx4 v[78:79], v[74:77], off
	s_nop 1
	v_pk_mul_f32 v[74:75], v[36:37], v[130:131] op_sel_hi:[1,0]
	v_pk_mul_f32 v[36:37], v[34:35], v[130:131] op_sel_hi:[1,0]
	v_cvt_pk_bf16_f32 v34, v38, v39
	v_cvt_pk_bf16_f32 v35, v40, v41
	s_nop 0
	v_cvt_pk_bf16_f32 v36, v36, v37
	v_cvt_pk_bf16_f32 v37, v74, v75
	global_store_dwordx4 v[78:79], v[34:37], off offset:256
	s_cbranch_execz .LBB0_192

; #define PG8_STAGE(bufoff, gbase, voff) do { _Pragma("unroll") for (int _i = 0; _i < 2; ++_i) \
;         __builtin_amdgcn_global_load_lds((const unsigned*)((const char*)(gbase) + (voff)[_i]), (PG8_LAS unsigned*)(lds + (bufoff) + ldsw + _i * 8192), 16, 0, 0); } while (0)
; #define PG8_LDA(dst, b, h) do { _Pragma("unroll") for (int m = 0; m < 4; ++m) _Pragma("unroll") for (int k = 0; k < 2; ++k) dst[m][k] = *(const PG8_LAS bf16x8*)(lds + PG8_SA(b, h) + aoff + m * 2048 + k * 1024); } while (0)
; #define PG8_LDB(dst, b, h) do { _Pragma("unroll") for (int n = 0; n < 2; ++n) _Pragma("unroll") for (int k = 0; k < 2; ++k) dst[n][k] = *(const PG8_LAS bf16x8*)(lds + PG8_SB(b, h) + boff + n * 2048 + k * 1024); } while (0)
; #define PG8_MMA(ai, bj, At, Bt) do { __builtin_amdgcn_s_setprio(1); _Pragma("unroll") for (int m = 0; m < 4; ++m) _Pragma("unroll") for (int n = 0; n < 2; ++n) _Pragma("unroll") for (int k = 0; k < 2; ++k) \
;         acc[ai][bj][m][n] = __builtin_amdgcn_mfma_f32_16x16x32_bf16(Bt[n][k], At[m][k], acc[ai][bj][m][n], 0, 0, 0); __builtin_amdgcn_s_setprio(0); } while (0)
; #define PG8_WAIT_V(n) asm volatile("s_waitcnt vmcnt(" #n ")" ::: "memory")
; #define PG8_WAIT_L(n) asm volatile("s_waitcnt lgkmcnt(" #n ")" ::: "memory")
; template <class Epi, class Sched, bool ALIGN_EPI = false, bool SP2 = false>
; __device__ __forceinline__ void gemm_phase(PG8_LAS unsigned char* lds, const Gemm g, const Sched& S, const Epi& E) {
;     ...
;             const bool last = (t == nt - 2);
;             const char* a1 = cA + (size_t)(t + 1) * kstep;
;             const char* a2 = last ? nA : cA + (size_t)(t + 2) * kstep; const char* b2 = last ? nB : cB + (size_t)(t + 2) * kstep;
;             const char* a3 = a2 + kstep; const char* b3 = b2 + kstep;
;             if (last && has_next) S.a_ready(nxt);
;             if constexpr (SP2) {
;             PG8_LDB(B0, 0, 0); PG8_LDB(B1, 0, 1); PG8_SCHED; PG8_LDA(At, 0, 0); PG8_STAGE(PG8_SA(1, 1), a1 + hstep, voffA);
;             PG8_WAIT_V(8); PG8_WAIT_L(0); PG8_BAR; PG8_MMA(0, 0, At, B0); PG8_MMA(0, 1, At, B1); PG8_BAR; PG8_SCHED;
;             PG8_LDA(At, 0, 1); PG8_STAGE(PG8_SB(0, 0), b2, voffB); PG8_STAGE(PG8_SB(0, 1), b2 + hstep, voffB); PG8_STAGE(PG8_SA(0, 0), a2, voffA);
;             PG8_WAIT_V(8); PG8_WAIT_L(0); PG8_BAR; PG8_MMA(1, 0, At, B0); PG8_MMA(1, 1, At, B1); PG8_BAR; PG8_SCHED;
.LBB0_812:
	s_add_u32 s26, s24, 0xfffc0080
	s_addc_u32 s27, s25, -1
	s_add_i32 s49, 0, 0x10000
	s_cmp_eq_u32 s48, 12
	s_cselect_b32 s29, s19, s27
	s_cselect_b32 s28, s33, s26
	v_add_u32_e32 v142, s49, v145
	s_cselect_b32 s27, s17, s47
	s_cselect_b32 s26, s45, s46
	s_add_i32 s52, 0, 0x14000
	s_cmp_lg_u32 s48, 0
	s_cbranch_scc1 .Levin_nopf
	s_cmp_lt_u32 s35, 0x1000
	s_cbranch_scc0 .Levin_nopf
	s_lshl_b32 s98, s5, 12
	s_add_u32 s98, s10, s98
	s_addc_u32 s99, s11, 0
	v_lshlrev_b32_e32 v232, 4, v174
	s_add_i32 m0, s35, 0x21000
	s_nop 0
	global_load_lds_dwordx4 v232, s[98:99]
.Levin_nopf:
	ds_read_b128 v[150:153], v142
	ds_read_b128 v[154:157], v142 offset:1024
	ds_read_b128 v[158:161], v142 offset:2048
	ds_read_b128 v[162:165], v142 offset:3072
	v_add_u32_e32 v142, s52, v145
	ds_read_b128 v[166:169], v142
	ds_read_b128 v[170:173], v142 offset:1024
	ds_read_b128 v[180:183], v142 offset:2048
	ds_read_b128 v[184:187], v142 offset:3072
	v_lshl_add_u64 v[146:147], s[24:25], 0, v[138:139]
	s_add_i32 m0, s36, 0xc000
	ds_read_b128 v[188:191], v149
	ds_read_b128 v[192:195], v149 offset:1024
	ds_read_b128 v[196:199], v149 offset:2048
	ds_read_b128 v[200:203], v149 offset:3072
	ds_read_b128 v[204:207], v149 offset:4096
	ds_read_b128 v[208:211], v149 offset:5120
	ds_read_b128 v[212:215], v149 offset:6144
	ds_read_b128 v[216:219], v149 offset:7168
	global_load_lds_dwordx4 v[146:147], off
	v_lshl_add_u64 v[146:147], s[24:25], 0, v[140:141]
	s_add_i32 m0, s36, 0xe000
	s_nop 0
	global_load_lds_dwordx4 v[146:147], off
	s_waitcnt vmcnt(8)
	s_waitcnt lgkmcnt(0)
	s_barrier
	s_setprio 1
	s_waitcnt lgkmcnt(0)
	v_mfma_f32_16x16x32_bf16 v[126:129], v[150:153], v[188:191], v[126:129]
	v_mfma_f32_16x16x32_bf16 v[122:125], v[158:161], v[188:191], v[122:125]
	v_mfma_f32_16x16x32_bf16 v[114:117], v[150:153], v[196:199], v[114:117]
	v_mfma_f32_16x16x32_bf16 v[106:109], v[158:161], v[196:199], v[106:109]
	v_mfma_f32_16x16x32_bf16 v[98:101], v[150:153], v[204:207], v[98:101]
	v_mfma_f32_16x16x32_bf16 v[90:93], v[158:161], v[204:207], v[90:93]
	v_mfma_f32_16x16x32_bf16 v[82:85], v[150:153], v[212:215], v[82:85]
	v_mfma_f32_16x16x32_bf16 v[74:77], v[158:161], v[212:215], v[74:77]
	v_mfma_f32_16x16x32_bf16 v[126:129], v[154:157], v[192:195], v[126:129]
	v_mfma_f32_16x16x32_bf16 v[122:125], v[162:165], v[192:195], v[122:125]
	v_mfma_f32_16x16x32_bf16 v[114:117], v[154:157], v[200:203], v[114:117]
	v_mfma_f32_16x16x32_bf16 v[106:109], v[162:165], v[200:203], v[106:109]
	v_mfma_f32_16x16x32_bf16 v[98:101], v[154:157], v[208:211], v[98:101]
	v_mfma_f32_16x16x32_bf16 v[90:93], v[162:165], v[208:211], v[90:93]
	v_mfma_f32_16x16x32_bf16 v[82:85], v[154:157], v[216:219], v[82:85]
	v_mfma_f32_16x16x32_bf16 v[74:77], v[162:165], v[216:219], v[74:77]
	s_setprio 0
	s_setprio 1
	v_mfma_f32_16x16x32_bf16 v[118:121], v[166:169], v[188:191], v[118:121]
	v_mfma_f32_16x16x32_bf16 v[110:113], v[180:183], v[188:191], v[110:113]
	v_mfma_f32_16x16x32_bf16 v[102:105], v[166:169], v[196:199], v[102:105]
	v_mfma_f32_16x16x32_bf16 v[94:97], v[180:183], v[196:199], v[94:97]
	v_mfma_f32_16x16x32_bf16 v[86:89], v[166:169], v[204:207], v[86:89]
	v_mfma_f32_16x16x32_bf16 v[78:81], v[180:183], v[204:207], v[78:81]
	v_mfma_f32_16x16x32_bf16 v[70:73], v[166:169], v[212:215], v[70:73]
	v_mfma_f32_16x16x32_bf16 v[66:69], v[180:183], v[212:215], v[66:69]
	v_mfma_f32_16x16x32_bf16 v[118:121], v[170:173], v[192:195], v[118:121]
	v_mfma_f32_16x16x32_bf16 v[110:113], v[184:187], v[192:195], v[110:113]
	v_mfma_f32_16x16x32_bf16 v[102:105], v[170:173], v[200:203], v[102:105]
	v_mfma_f32_16x16x32_bf16 v[94:97], v[184:187], v[200:203], v[94:97]
	v_mfma_f32_16x16x32_bf16 v[86:89], v[170:173], v[208:211], v[86:89]
	v_mfma_f32_16x16x32_bf16 v[78:81], v[184:187], v[208:211], v[78:81]
	v_mfma_f32_16x16x32_bf16 v[70:73], v[170:173], v[216:219], v[70:73]
	v_mfma_f32_16x16x32_bf16 v[66:69], v[184:187], v[216:219], v[66:69]
	s_setprio 0
	s_barrier
	s_add_i32 s49, s49, s35
	v_lshl_add_u64 v[146:147], s[26:27], 0, v[134:135]
	s_mov_b32 m0, s49
	ds_read_b128 v[188:191], v149 offset:16384
	ds_read_b128 v[192:195], v149 offset:17408
	ds_read_b128 v[196:199], v149 offset:18432
	ds_read_b128 v[200:203], v149 offset:19456
	ds_read_b128 v[204:207], v149 offset:20480
	ds_read_b128 v[208:211], v149 offset:21504
	ds_read_b128 v[212:215], v149 offset:22528
	ds_read_b128 v[216:219], v149 offset:23552
	global_load_lds_dwordx4 v[146:147], off
	s_add_i32 m0, s49, 0x2000
	s_add_u32 s50, s26, 0x40000
	v_lshl_add_u64 v[220:221], s[26:27], 0, v[130:131]
	s_addc_u32 s51, s27, 0
	s_add_i32 s49, s52, s35
	global_load_lds_dwordx4 v[220:221], off
	v_lshl_add_u64 v[222:223], s[50:51], 0, v[134:135]
	s_mov_b32 m0, s49
	v_lshl_add_u64 v[228:229], s[28:29], 0, v[132:133]
	global_load_lds_dwordx4 v[222:223], off
	v_lshl_add_u64 v[222:223], s[50:51], 0, v[130:131]
	s_add_i32 m0, s49, 0x2000
	s_nop 0
	global_load_lds_dwordx4 v[222:223], off
	v_lshl_add_u64 v[222:223], s[28:29], 0, v[136:137]
	s_mov_b32 m0, s36
	s_nop 0
	global_load_lds_dwordx4 v[222:223], off
	s_mov_b32 m0, s37
	s_nop 0
	global_load_lds_dwordx4 v[228:229], off
	s_waitcnt vmcnt(8)
	s_waitcnt lgkmcnt(0)
	s_barrier
; #define PG8_STAGE(bufoff, gbase, voff) do { _Pragma("unroll") for (int _i = 0; _i < 2; ++_i) \
;         __builtin_amdgcn_global_load_lds((const unsigned*)((const char*)(gbase) + (voff)[_i]), (PG8_LAS unsigned*)(lds + (bufoff) + ldsw + _i * 8192), 16, 0, 0); } while (0)
; #define PG8_LDA(dst, b, h) do { _Pragma("unroll") for (int m = 0; m < 4; ++m) _Pragma("unroll") for (int k = 0; k < 2; ++k) dst[m][k] = *(const PG8_LAS bf16x8*)(lds + PG8_SA(b, h) + aoff + m * 2048 + k * 1024); } while (0)
; #define PG8_LDB(dst, b, h) do { _Pragma("unroll") for (int n = 0; n < 2; ++n) _Pragma("unroll") for (int k = 0; k < 2; ++k) dst[n][k] = *(const PG8_LAS bf16x8*)(lds + PG8_SB(b, h) + boff + n * 2048 + k * 1024); } while (0)
; #define PG8_MMA(ai, bj, At, Bt) do { __builtin_amdgcn_s_setprio(1); _Pragma("unroll") for (int m = 0; m < 4; ++m) _Pragma("unroll") for (int n = 0; n < 2; ++n) _Pragma("unroll") for (int k = 0; k < 2; ++k) \
;         acc[ai][bj][m][n] = __builtin_amdgcn_mfma_f32_16x16x32_bf16(Bt[n][k], At[m][k], acc[ai][bj][m][n], 0, 0, 0); __builtin_amdgcn_s_setprio(0); } while (0)
; #define PG8_WAIT_V(n) asm volatile("s_waitcnt vmcnt(" #n ")" ::: "memory")
; #define PG8_WAIT_L(n) asm volatile("s_waitcnt lgkmcnt(" #n ")" ::: "memory")
; #define PG8_BAR __builtin_amdgcn_s_barrier()
; #define PG8_SCHED __builtin_amdgcn_sched_barrier(0)
; template <class Epi, class Sched, bool ALIGN_EPI = false, bool SP2 = false>
; __device__ __forceinline__ void gemm_phase(PG8_LAS unsigned char* lds, const Gemm g, const Sched& S, const Epi& E) {
;     ...
;             PG8_WAIT_V(8); PG8_WAIT_L(0); PG8_BAR; PG8_MMA(0, 0, At, B0); PG8_MMA(0, 1, At, B1); PG8_BAR; PG8_SCHED;
;             PG8_LDA(At, 0, 1); PG8_STAGE(PG8_SB(0, 0), b2, voffB); PG8_STAGE(PG8_SB(0, 1), b2 + hstep, voffB); PG8_STAGE(PG8_SA(0, 0), a2, voffA);
;             PG8_WAIT_V(8); PG8_WAIT_L(0); PG8_BAR; PG8_MMA(1, 0, At, B0); PG8_MMA(1, 1, At, B1); PG8_BAR; PG8_SCHED;
;             PG8_LDB(B0, 1, 0); PG8_LDB(B1, 1, 1); PG8_SCHED; PG8_LDA(At, 1, 0); PG8_STAGE(PG8_SA(0, 1), a2 + hstep, voffA);
;             PG8_WAIT_V(8); PG8_WAIT_L(0); PG8_BAR; PG8_MMA(0, 0, At, B0); PG8_MMA(0, 1, At, B1); PG8_BAR; PG8_SCHED;
	s_setprio 1
	s_waitcnt lgkmcnt(0)
	v_mfma_f32_16x16x32_bf16 v[62:65], v[150:153], v[188:191], v[62:65]
	v_mfma_f32_16x16x32_bf16 v[58:61], v[158:161], v[188:191], v[58:61]
	v_mfma_f32_16x16x32_bf16 v[50:53], v[150:153], v[196:199], v[50:53]
	v_mfma_f32_16x16x32_bf16 v[42:45], v[158:161], v[196:199], v[42:45]
	v_mfma_f32_16x16x32_bf16 v[34:37], v[150:153], v[204:207], v[34:37]
	v_mfma_f32_16x16x32_bf16 v[26:29], v[158:161], v[204:207], v[26:29]
	v_mfma_f32_16x16x32_bf16 v[18:21], v[150:153], v[212:215], v[18:21]
	v_mfma_f32_16x16x32_bf16 v[10:13], v[158:161], v[212:215], v[10:13]
	v_mfma_f32_16x16x32_bf16 v[62:65], v[154:157], v[192:195], v[62:65]
	v_mfma_f32_16x16x32_bf16 v[58:61], v[162:165], v[192:195], v[58:61]
	v_mfma_f32_16x16x32_bf16 v[50:53], v[154:157], v[200:203], v[50:53]
	v_mfma_f32_16x16x32_bf16 v[42:45], v[162:165], v[200:203], v[42:45]
	v_mfma_f32_16x16x32_bf16 v[34:37], v[154:157], v[208:211], v[34:37]
	v_mfma_f32_16x16x32_bf16 v[26:29], v[162:165], v[208:211], v[26:29]
	v_mfma_f32_16x16x32_bf16 v[18:21], v[154:157], v[216:219], v[18:21]
	v_mfma_f32_16x16x32_bf16 v[10:13], v[162:165], v[216:219], v[10:13]
	s_setprio 0
	s_setprio 1
	v_mfma_f32_16x16x32_bf16 v[54:57], v[166:169], v[188:191], v[54:57]
	v_mfma_f32_16x16x32_bf16 v[46:49], v[180:183], v[188:191], v[46:49]
	v_mfma_f32_16x16x32_bf16 v[38:41], v[166:169], v[196:199], v[38:41]
	v_mfma_f32_16x16x32_bf16 v[30:33], v[180:183], v[196:199], v[30:33]
	v_mfma_f32_16x16x32_bf16 v[22:25], v[166:169], v[204:207], v[22:25]
	v_mfma_f32_16x16x32_bf16 v[14:17], v[180:183], v[204:207], v[14:17]
	v_mfma_f32_16x16x32_bf16 v[6:9], v[166:169], v[212:215], v[6:9]
	v_mfma_f32_16x16x32_bf16 v[2:5], v[180:183], v[212:215], v[2:5]
	v_mfma_f32_16x16x32_bf16 v[54:57], v[170:173], v[192:195], v[54:57]
	v_mfma_f32_16x16x32_bf16 v[46:49], v[184:187], v[192:195], v[46:49]
	v_mfma_f32_16x16x32_bf16 v[38:41], v[170:173], v[200:203], v[38:41]
	v_mfma_f32_16x16x32_bf16 v[30:33], v[184:187], v[200:203], v[30:33]
	v_mfma_f32_16x16x32_bf16 v[22:25], v[170:173], v[208:211], v[22:25]
	v_mfma_f32_16x16x32_bf16 v[14:17], v[184:187], v[208:211], v[14:17]
	v_mfma_f32_16x16x32_bf16 v[6:9], v[170:173], v[216:219], v[6:9]
	v_mfma_f32_16x16x32_bf16 v[2:5], v[184:187], v[216:219], v[2:5]
	s_setprio 0
	s_barrier
	s_add_i32 s49, 0, 0x18000
	v_add_u32_e32 v142, s49, v145
	s_add_i32 s50, 0, 0x1c000
	ds_read_b128 v[150:153], v142
	ds_read_b128 v[154:157], v142 offset:1024
	ds_read_b128 v[158:161], v142 offset:2048
	ds_read_b128 v[162:165], v142 offset:3072
	v_add_u32_e32 v142, s50, v145
	ds_read_b128 v[166:169], v142
	ds_read_b128 v[170:173], v142 offset:1024
	ds_read_b128 v[180:183], v142 offset:2048
	ds_read_b128 v[184:187], v142 offset:3072
	s_add_u32 s28, s28, 0x40000
	s_addc_u32 s29, s29, 0
	s_mov_b32 m0, s38
	v_lshl_add_u64 v[230:231], s[28:29], 0, v[136:137]
	ds_read_b128 v[188:191], v149 offset:32768
	ds_read_b128 v[192:195], v149 offset:33792
	ds_read_b128 v[196:199], v149 offset:34816
	ds_read_b128 v[200:203], v149 offset:35840
	ds_read_b128 v[204:207], v149 offset:36864
	ds_read_b128 v[208:211], v149 offset:37888
	ds_read_b128 v[212:215], v149 offset:38912
	ds_read_b128 v[216:219], v149 offset:39936
	global_load_lds_dwordx4 v[230:231], off
	v_lshl_add_u64 v[230:231], s[28:29], 0, v[132:133]
	s_mov_b32 m0, s39
	s_nop 0
	global_load_lds_dwordx4 v[230:231], off
	s_waitcnt vmcnt(8)
	s_waitcnt lgkmcnt(0)
	s_barrier
	s_setprio 1
	s_waitcnt lgkmcnt(0)
	v_mfma_f32_16x16x32_bf16 v[126:129], v[150:153], v[188:191], v[126:129]
	v_mfma_f32_16x16x32_bf16 v[122:125], v[158:161], v[188:191], v[122:125]
	v_mfma_f32_16x16x32_bf16 v[114:117], v[150:153], v[196:199], v[114:117]
	v_mfma_f32_16x16x32_bf16 v[106:109], v[158:161], v[196:199], v[106:109]
	v_mfma_f32_16x16x32_bf16 v[98:101], v[150:153], v[204:207], v[98:101]
	v_mfma_f32_16x16x32_bf16 v[90:93], v[158:161], v[204:207], v[90:93]
	v_mfma_f32_16x16x32_bf16 v[82:85], v[150:153], v[212:215], v[82:85]
	v_mfma_f32_16x16x32_bf16 v[74:77], v[158:161], v[212:215], v[74:77]
	v_mfma_f32_16x16x32_bf16 v[126:129], v[154:157], v[192:195], v[126:129]
	v_mfma_f32_16x16x32_bf16 v[122:125], v[162:165], v[192:195], v[122:125]
	v_mfma_f32_16x16x32_bf16 v[114:117], v[154:157], v[200:203], v[114:117]
	v_mfma_f32_16x16x32_bf16 v[106:109], v[162:165], v[200:203], v[106:109]
	v_mfma_f32_16x16x32_bf16 v[98:101], v[154:157], v[208:211], v[98:101]
	v_mfma_f32_16x16x32_bf16 v[90:93], v[162:165], v[208:211], v[90:93]
	v_mfma_f32_16x16x32_bf16 v[82:85], v[154:157], v[216:219], v[82:85]
	v_mfma_f32_16x16x32_bf16 v[74:77], v[162:165], v[216:219], v[74:77]
	s_setprio 0
	s_setprio 1
	v_mfma_f32_16x16x32_bf16 v[118:121], v[166:169], v[188:191], v[118:121]
	v_mfma_f32_16x16x32_bf16 v[110:113], v[180:183], v[188:191], v[110:113]
	v_mfma_f32_16x16x32_bf16 v[102:105], v[166:169], v[196:199], v[102:105]
	v_mfma_f32_16x16x32_bf16 v[94:97], v[180:183], v[196:199], v[94:97]
	v_mfma_f32_16x16x32_bf16 v[86:89], v[166:169], v[204:207], v[86:89]
	v_mfma_f32_16x16x32_bf16 v[78:81], v[180:183], v[204:207], v[78:81]
	v_mfma_f32_16x16x32_bf16 v[70:73], v[166:169], v[212:215], v[70:73]
	v_mfma_f32_16x16x32_bf16 v[66:69], v[180:183], v[212:215], v[66:69]
	v_mfma_f32_16x16x32_bf16 v[118:121], v[170:173], v[192:195], v[118:121]
	v_mfma_f32_16x16x32_bf16 v[110:113], v[184:187], v[192:195], v[110:113]
	v_mfma_f32_16x16x32_bf16 v[102:105], v[170:173], v[200:203], v[102:105]
	v_mfma_f32_16x16x32_bf16 v[94:97], v[184:187], v[200:203], v[94:97]
	v_mfma_f32_16x16x32_bf16 v[86:89], v[170:173], v[208:211], v[86:89]
	v_mfma_f32_16x16x32_bf16 v[78:81], v[184:187], v[208:211], v[78:81]
	v_mfma_f32_16x16x32_bf16 v[70:73], v[170:173], v[216:219], v[70:73]
	v_mfma_f32_16x16x32_bf16 v[66:69], v[184:187], v[216:219], v[66:69]
	s_setprio 0
	s_barrier
; #define PG8_STAGE(bufoff, gbase, voff) do { _Pragma("unroll") for (int _i = 0; _i < 2; ++_i) \
;         __builtin_amdgcn_global_load_lds((const unsigned*)((const char*)(gbase) + (voff)[_i]), (PG8_LAS unsigned*)(lds + (bufoff) + ldsw + _i * 8192), 16, 0, 0); } while (0)
; #define PG8_LDA(dst, b, h) do { _Pragma("unroll") for (int m = 0; m < 4; ++m) _Pragma("unroll") for (int k = 0; k < 2; ++k) dst[m][k] = *(const PG8_LAS bf16x8*)(lds + PG8_SA(b, h) + aoff + m * 2048 + k * 1024); } while (0)
; #define PG8_MMA(ai, bj, At, Bt) do { __builtin_amdgcn_s_setprio(1); _Pragma("unroll") for (int m = 0; m < 4; ++m) _Pragma("unroll") for (int n = 0; n < 2; ++n) _Pragma("unroll") for (int k = 0; k < 2; ++k) \
;         acc[ai][bj][m][n] = __builtin_amdgcn_mfma_f32_16x16x32_bf16(Bt[n][k], At[m][k], acc[ai][bj][m][n], 0, 0, 0); __builtin_amdgcn_s_setprio(0); } while (0)
; #define PG8_WAIT_V(n) asm volatile("s_waitcnt vmcnt(" #n ")" ::: "memory")
; #define PG8_WAIT_L(n) asm volatile("s_waitcnt lgkmcnt(" #n ")" ::: "memory")
; #define PG8_BAR __builtin_amdgcn_s_barrier()
; #define PG8_SCHED __builtin_amdgcn_sched_barrier(0)
;     __device__ __forceinline__ void operator()(const f32x4 (&acc)[2][2][4][2], const Unit& u, int wr, int wc, int fr, int fq) const {
;     ...
;         int colt = u.pn * BM; bf16_t* base = O; float sc = 1.f;
;         if (split_cols) { const int t = colt / split_cols; base += (size_t)t * split_stride; colt -= t * split_cols; if (t == 0) sc = scale0; }
;         const int col0 = colt + wc * 32 + 8 * fq;
;         float rsv[2][4];
; #pragma unroll
;         for (int ai = 0; ai < 2; ++ai)
; #pragma unroll
;             for (int m = 0; m < 4; ++m) rsv[ai][m] = row_rstd(ssq, row0 + ai * HALF + m * 16 + row_off) * sc;
; template <class Epi, class Sched, bool ALIGN_EPI = false, bool SP2 = false>
; __device__ __forceinline__ void gemm_phase(PG8_LAS unsigned char* lds, const Gemm g, const Sched& S, const Epi& E) {
;     ...
;             PG8_LDA(At, 1, 1); PG8_STAGE(PG8_SB(1, 0), b3, voffB); PG8_STAGE(PG8_SB(1, 1), b3 + hstep, voffB); PG8_STAGE(PG8_SA(1, 0), a3, voffA);
;             PG8_WAIT_V(8); PG8_WAIT_L(0); PG8_BAR; PG8_MMA(1, 0, At, B0); PG8_MMA(1, 1, At, B1); PG8_BAR; PG8_SCHED;
	s_add_i32 s28, s49, s35
	v_lshl_add_u64 v[146:147], v[146:147], 0, s[96:97]
	s_mov_b32 m0, s28
	ds_read_b128 v[188:191], v149 offset:49152
	ds_read_b128 v[192:195], v149 offset:50176
	ds_read_b128 v[196:199], v149 offset:51200
	ds_read_b128 v[200:203], v149 offset:52224
	ds_read_b128 v[204:207], v149 offset:53248
	ds_read_b128 v[208:211], v149 offset:54272
	ds_read_b128 v[212:215], v149 offset:55296
	ds_read_b128 v[216:219], v149 offset:56320
	global_load_lds_dwordx4 v[146:147], off
	s_add_i32 m0, s28, 0x2000
	s_add_u32 s26, s26, 0x40080
	v_lshl_add_u64 v[146:147], v[220:221], 0, s[96:97]
	s_addc_u32 s27, s27, 0
	s_add_i32 s28, s50, s35
	global_load_lds_dwordx4 v[146:147], off
	v_lshl_add_u64 v[146:147], s[26:27], 0, v[134:135]
	s_mov_b32 m0, s28
	s_nop 0
	global_load_lds_dwordx4 v[146:147], off
	v_lshl_add_u64 v[146:147], s[26:27], 0, v[130:131]
	s_add_i32 m0, s28, 0x2000
	s_nop 0
	global_load_lds_dwordx4 v[146:147], off
	v_lshl_add_u64 v[146:147], v[222:223], 0, s[96:97]
	s_mov_b32 m0, s42
	s_nop 0
	global_load_lds_dwordx4 v[146:147], off
	v_lshl_add_u64 v[146:147], v[228:229], 0, s[96:97]
	s_mov_b32 m0, s43
	s_nop 0
	global_load_lds_dwordx4 v[146:147], off
	s_waitcnt vmcnt(8)
	s_waitcnt lgkmcnt(0)
	s_barrier
	s_setprio 1
	s_waitcnt lgkmcnt(0)
	v_mfma_f32_16x16x32_bf16 v[62:65], v[150:153], v[188:191], v[62:65]
	v_mfma_f32_16x16x32_bf16 v[58:61], v[158:161], v[188:191], v[58:61]
	v_mfma_f32_16x16x32_bf16 v[50:53], v[150:153], v[196:199], v[50:53]
	v_mfma_f32_16x16x32_bf16 v[42:45], v[158:161], v[196:199], v[42:45]
	v_mfma_f32_16x16x32_bf16 v[34:37], v[150:153], v[204:207], v[34:37]
	v_mfma_f32_16x16x32_bf16 v[26:29], v[158:161], v[204:207], v[26:29]
	v_mfma_f32_16x16x32_bf16 v[18:21], v[150:153], v[212:215], v[18:21]
	v_mfma_f32_16x16x32_bf16 v[10:13], v[158:161], v[212:215], v[10:13]
	v_mfma_f32_16x16x32_bf16 v[62:65], v[154:157], v[192:195], v[62:65]
	v_mfma_f32_16x16x32_bf16 v[58:61], v[162:165], v[192:195], v[58:61]
	v_mfma_f32_16x16x32_bf16 v[50:53], v[154:157], v[200:203], v[50:53]
	v_mfma_f32_16x16x32_bf16 v[42:45], v[162:165], v[200:203], v[42:45]
	v_mfma_f32_16x16x32_bf16 v[34:37], v[154:157], v[208:211], v[34:37]
	v_mfma_f32_16x16x32_bf16 v[26:29], v[162:165], v[208:211], v[26:29]
	v_mfma_f32_16x16x32_bf16 v[18:21], v[154:157], v[216:219], v[18:21]
	v_mfma_f32_16x16x32_bf16 v[10:13], v[162:165], v[216:219], v[10:13]
	s_setprio 0
	s_setprio 1
	v_mfma_f32_16x16x32_bf16 v[54:57], v[166:169], v[188:191], v[54:57]
	v_mfma_f32_16x16x32_bf16 v[46:49], v[180:183], v[188:191], v[46:49]
	v_mfma_f32_16x16x32_bf16 v[38:41], v[166:169], v[196:199], v[38:41]
	v_mfma_f32_16x16x32_bf16 v[30:33], v[180:183], v[196:199], v[30:33]
	v_mfma_f32_16x16x32_bf16 v[22:25], v[166:169], v[204:207], v[22:25]
	v_mfma_f32_16x16x32_bf16 v[14:17], v[180:183], v[204:207], v[14:17]
	v_mfma_f32_16x16x32_bf16 v[6:9], v[166:169], v[212:215], v[6:9]
	v_mfma_f32_16x16x32_bf16 v[2:5], v[180:183], v[212:215], v[2:5]
	v_mfma_f32_16x16x32_bf16 v[54:57], v[170:173], v[192:195], v[54:57]
	v_mfma_f32_16x16x32_bf16 v[46:49], v[184:187], v[192:195], v[46:49]
	v_mfma_f32_16x16x32_bf16 v[38:41], v[170:173], v[200:203], v[38:41]
	v_mfma_f32_16x16x32_bf16 v[30:33], v[184:187], v[200:203], v[30:33]
	v_mfma_f32_16x16x32_bf16 v[22:25], v[170:173], v[208:211], v[22:25]
	v_mfma_f32_16x16x32_bf16 v[14:17], v[184:187], v[208:211], v[14:17]
	v_mfma_f32_16x16x32_bf16 v[6:9], v[170:173], v[216:219], v[6:9]
	v_mfma_f32_16x16x32_bf16 v[2:5], v[184:187], v[216:219], v[2:5]
	s_setprio 0
	s_barrier
	s_add_i32 s48, s48, 2
	s_add_u32 s24, s24, 0x100
	s_addc_u32 s25, s25, 0
	s_add_u32 s46, s46, 0x100
	s_addc_u32 s47, s47, 0
	s_cmp_gt_u32 s48, 13
	s_cbranch_scc0 .LBB0_812
	s_and_b64 vcc, exec, s[14:15]
	s_cbranch_vccz .LBB0_815
	s_barrier
.LBB0_815:
	v_add_u32_e32 v233, s40, v1
	v_lshlrev_b32_e32 v233, 4, v233
	v_add_u32_e32 v233, 0x21000, v233
	v_mov_b32_e32 v142, v1
	v_mov_b32_e32 v153, v143
	s_cmp_eq_u32 s4, -1
	s_cbranch_scc1 .LBB0_817
	s_lshl_b32 s5, s5, 8
	s_add_i32 s5, s5, s40
	v_add_u32_e32 v170, s5, v142
	v_ashrrev_i32_e32 v171, 31, v170
	ds_read_b128 v[154:157], v233
	v_add_u32_e32 v168, 16, v170
	v_ashrrev_i32_e32 v169, 31, v168
	v_add_u32_e32 v166, 32, v170
	v_ashrrev_i32_e32 v167, 31, v166
	v_add_u32_e32 v164, 48, v170
	v_ashrrev_i32_e32 v165, 31, v164
	v_add_u32_e32 v150, 0xa0, v170
	v_ashrrev_i32_e32 v151, 31, v150
	s_lshl_b32 s4, s4, 8
	s_or_b32 s4, s4, s41
	s_waitcnt lgkmcnt(0)
	v_mov_b32_e32 v146, v155
	v_mov_b32_e32 v147, v156
	v_mov_b32_e32 v155, v157
	v_pk_add_f32 v[146:147], v[146:147], v[154:155]
	s_nop 0
	v_add_f32_e32 v142, v146, v147
	ds_read_b128 v[154:157], v233 offset:256
	v_fmamk_f32 v142, v142, 0x3a800000, v175
	v_rsq_f32_e32 v162, v142
	s_waitcnt lgkmcnt(0)
	v_mov_b32_e32 v146, v155
	v_mov_b32_e32 v147, v156
	v_mov_b32_e32 v155, v157
	v_pk_add_f32 v[146:147], v[146:147], v[154:155]
	v_pk_mul_f32 v[128:129], v[128:129], v[162:163] op_sel_hi:[1,0]
	v_add_f32_e32 v142, v146, v147
	ds_read_b128 v[154:157], v233 offset:512
	v_fmamk_f32 v142, v142, 0x3a800000, v175
	v_rsq_f32_e32 v160, v142
	v_pk_mul_f32 v[126:127], v[126:127], v[162:163] op_sel_hi:[1,0]
	v_pk_mul_f32 v[120:121], v[120:121], v[162:163] op_sel_hi:[1,0]
	v_pk_mul_f32 v[118:119], v[118:119], v[162:163] op_sel_hi:[1,0]
	v_pk_mul_f32 v[114:115], v[114:115], v[160:161] op_sel_hi:[1,0]
	v_pk_mul_f32 v[104:105], v[104:105], v[160:161] op_sel_hi:[1,0]
	v_pk_mul_f32 v[102:103], v[102:103], v[160:161] op_sel_hi:[1,0]
	s_waitcnt lgkmcnt(0)
	v_mov_b32_e32 v146, v155
	v_mov_b32_e32 v147, v156
	v_mov_b32_e32 v155, v157
	v_pk_add_f32 v[146:147], v[146:147], v[154:155]
	s_nop 0
	v_add_f32_e32 v142, v146, v147
	ds_read_b128 v[156:159], v233 offset:768
	v_fmamk_f32 v142, v142, 0x3a800000, v175
	v_rsq_f32_e32 v154, v142
	s_waitcnt lgkmcnt(0)
;     __device__ __forceinline__ void operator()(const f32x4 (&acc)[2][2][4][2], const Unit& u, int wr, int wc, int fr, int fq) const {
;     ...
;         float rsv[2][4];
; #pragma unroll
;         for (int ai = 0; ai < 2; ++ai)
; #pragma unroll
;             for (int m = 0; m < 4; ++m) rsv[ai][m] = row_rstd(ssq, row0 + ai * HALF + m * 16 + row_off) * sc;
	v_mov_b32_e32 v146, v157
	v_mov_b32_e32 v147, v158
	v_mov_b32_e32 v157, v159
	v_add_u32_e32 v158, 0x80, v170
	v_pk_add_f32 v[146:147], v[146:147], v[156:157]
	v_ashrrev_i32_e32 v159, 31, v158
	v_add_f32_e32 v142, v146, v147
	ds_read_b128 v[180:183], v233 offset:2048
	v_add_u32_e32 v156, 0x90, v170
	v_fmamk_f32 v142, v142, 0x3a800000, v175
	v_ashrrev_i32_e32 v157, 31, v156
	v_rsq_f32_e32 v152, v142
	s_waitcnt lgkmcnt(0)
	v_mov_b32_e32 v146, v181
	v_mov_b32_e32 v147, v182
	v_mov_b32_e32 v181, v183
	v_pk_add_f32 v[146:147], v[146:147], v[180:181]
	v_pk_mul_f32 v[82:83], v[82:83], v[152:153] op_sel_hi:[1,0]
	v_add_f32_e32 v142, v146, v147
	ds_read_b128 v[180:183], v233 offset:2304
	v_fmamk_f32 v142, v142, 0x3a800000, v175
	v_rsq_f32_e32 v148, v142
	v_pk_mul_f32 v[72:73], v[72:73], v[152:153] op_sel_hi:[1,0]
	v_pk_mul_f32 v[70:71], v[70:71], v[152:153] op_sel_hi:[1,0]
	v_pk_mul_f32 v[64:65], v[64:65], v[148:149] op_sel_hi:[1,0]
	v_pk_mul_f32 v[62:63], v[62:63], v[148:149] op_sel_hi:[1,0]
	v_pk_mul_f32 v[56:57], v[56:57], v[148:149] op_sel_hi:[1,0]
	v_pk_mul_f32 v[54:55], v[54:55], v[148:149] op_sel_hi:[1,0]
	s_waitcnt lgkmcnt(0)
	v_mov_b32_e32 v146, v181
	v_mov_b32_e32 v147, v182
	v_mov_b32_e32 v181, v183
	v_pk_add_f32 v[146:147], v[146:147], v[180:181]
	s_nop 0
	v_add_f32_e32 v142, v146, v147
	ds_read_b128 v[180:183], v233 offset:2560
	v_fmamk_f32 v142, v142, 0x3a800000, v175
	v_rsq_f32_e32 v144, v142
	s_waitcnt lgkmcnt(0)
	v_mov_b32_e32 v146, v181
	v_mov_b32_e32 v147, v182
	v_mov_b32_e32 v181, v183
	v_pk_add_f32 v[146:147], v[146:147], v[180:181]
	v_pk_mul_f32 v[50:51], v[50:51], v[144:145] op_sel_hi:[1,0]
	v_add_f32_e32 v142, v146, v147
	v_add_u32_e32 v146, 0xb0, v170
	v_ashrrev_i32_e32 v147, 31, v146
	ds_read_b128 v[180:183], v233 offset:2816
	v_lshlrev_b64 v[170:171], 12, v[170:171]
	v_fmamk_f32 v142, v142, 0x3a800000, v175
	v_rsq_f32_e32 v142, v142
	v_pk_mul_f32 v[40:41], v[40:41], v[144:145] op_sel_hi:[1,0]
	v_pk_mul_f32 v[38:39], v[38:39], v[144:145] op_sel_hi:[1,0]
	v_pk_mul_f32 v[34:35], v[34:35], v[142:143] op_sel_hi:[1,0]
	v_pk_mul_f32 v[24:25], v[24:25], v[142:143] op_sel_hi:[1,0]
	v_pk_mul_f32 v[22:23], v[22:23], v[142:143] op_sel_hi:[1,0]
	s_waitcnt lgkmcnt(0)
; __device__ __forceinline__ unsigned cvt_pk_bf16(float lo, float hi) { unsigned r; asm volatile("v_cvt_pk_bf16_f32 %0, %1, %2" : "=v"(r) : "v"(lo), "v"(hi)); return r; }
;     __device__ __forceinline__ void operator()(const f32x4 (&acc)[2][2][4][2], const Unit& u, int wr, int wc, int fr, int fq) const {
;     ...
; #pragma unroll
;         for (int ai = 0; ai < 2; ++ai)
; #pragma unroll
;             for (int m = 0; m < 4; ++m) { const int row = row0 + ai * HALF + m * 16; const float rs = rsv[ai][m]; bf16_t* rowp = base + (size_t)row * ldc + col0;
; #pragma unroll
;                 for (int bj = 0; bj < 2; ++bj) { const f32x4 v0 = acc[ai][bj][m][0] * rs, v1 = acc[ai][bj][m][1] * rs;
;                     u32x4 w; w.x = cvt_pk_bf16(v0[0], v0[1]); w.y = cvt_pk_bf16(v0[2], v0[3]); w.z = cvt_pk_bf16(v1[0], v1[1]); w.w = cvt_pk_bf16(v1[2], v1[3]);
;                     *(u32x4*)(rowp + bj * HALF) = w; } asm volatile("" ::: "memory"); }
	v_mov_b32_e32 v172, v181
	v_mov_b32_e32 v173, v182
	v_mov_b32_e32 v181, v183
	v_pk_add_f32 v[172:173], v[172:173], v[180:181]
	v_lshl_add_u32 v180, v153, 3, s4
	v_ashrrev_i32_e32 v181, 31, v180
	v_lshl_add_u64 v[180:181], v[180:181], 1, s[12:13]
	v_lshl_add_u64 v[170:171], v[180:181], 0, v[170:171]
	v_pk_mul_f32 v[182:183], v[124:125], v[162:163] op_sel_hi:[1,0]
	v_pk_mul_f32 v[124:125], v[122:123], v[162:163] op_sel_hi:[1,0]
	v_cvt_pk_bf16_f32 v122, v126, v127
	v_cvt_pk_bf16_f32 v123, v128, v129
	v_add_f32_e32 v155, v172, v173
	v_cvt_pk_bf16_f32 v124, v124, v125
	v_cvt_pk_bf16_f32 v125, v182, v183
	global_store_dwordx4 v[170:171], v[122:125], off
	v_fmamk_f32 v155, v155, 0x3a800000, v175
	v_pk_mul_f32 v[98:99], v[98:99], v[154:155] op_sel_hi:[1,0]
	v_pk_mul_f32 v[122:123], v[112:113], v[162:163] op_sel_hi:[1,0]
	v_pk_mul_f32 v[112:113], v[110:111], v[162:163] op_sel_hi:[1,0]
	v_cvt_pk_bf16_f32 v110, v118, v119
	v_cvt_pk_bf16_f32 v111, v120, v121
	v_pk_mul_f32 v[88:89], v[88:89], v[154:155] op_sel_hi:[1,0]
	v_cvt_pk_bf16_f32 v112, v112, v113
	v_cvt_pk_bf16_f32 v113, v122, v123
	global_store_dwordx4 v[170:171], v[110:113], off offset:256
	v_pk_mul_f32 v[86:87], v[86:87], v[154:155] op_sel_hi:[1,0]
	v_rsq_f32_e32 v172, v155
	v_lshlrev_b64 v[110:111], 12, v[168:169]
	v_lshl_add_u64 v[110:111], v[180:181], 0, v[110:111]
	v_pk_mul_f32 v[112:113], v[116:117], v[160:161] op_sel_hi:[1,0]
	v_pk_mul_f32 v[116:117], v[108:109], v[160:161] op_sel_hi:[1,0]
	v_pk_mul_f32 v[108:109], v[106:107], v[160:161] op_sel_hi:[1,0]
	v_cvt_pk_bf16_f32 v106, v114, v115
	v_cvt_pk_bf16_f32 v107, v112, v113
	v_pk_mul_f32 v[18:19], v[18:19], v[172:173] op_sel_hi:[1,0]
	v_cvt_pk_bf16_f32 v108, v108, v109
	v_cvt_pk_bf16_f32 v109, v116, v117
	global_store_dwordx4 v[110:111], v[106:109], off
	v_pk_mul_f32 v[8:9], v[8:9], v[172:173] op_sel_hi:[1,0]
	v_pk_mul_f32 v[6:7], v[6:7], v[172:173] op_sel_hi:[1,0]
	v_pk_mul_f32 v[106:107], v[96:97], v[160:161] op_sel_hi:[1,0]
	v_pk_mul_f32 v[96:97], v[94:95], v[160:161] op_sel_hi:[1,0]
	v_cvt_pk_bf16_f32 v94, v102, v103
	v_cvt_pk_bf16_f32 v95, v104, v105
	s_nop 0
	v_cvt_pk_bf16_f32 v96, v96, v97
	v_cvt_pk_bf16_f32 v97, v106, v107
	global_store_dwordx4 v[110:111], v[94:97], off offset:256
	s_nop 1
	v_lshlrev_b64 v[94:95], 12, v[166:167]
	v_lshl_add_u64 v[94:95], v[180:181], 0, v[94:95]
	v_pk_mul_f32 v[96:97], v[100:101], v[154:155] op_sel_hi:[1,0]
	v_pk_mul_f32 v[100:101], v[92:93], v[154:155] op_sel_hi:[1,0]
	v_pk_mul_f32 v[92:93], v[90:91], v[154:155] op_sel_hi:[1,0]
	v_cvt_pk_bf16_f32 v90, v98, v99
	v_cvt_pk_bf16_f32 v91, v96, v97
	s_nop 0
	v_cvt_pk_bf16_f32 v92, v92, v93
	v_cvt_pk_bf16_f32 v93, v100, v101
	global_store_dwordx4 v[94:95], v[90:93], off
	s_nop 1
	v_pk_mul_f32 v[90:91], v[80:81], v[154:155] op_sel_hi:[1,0]
	v_pk_mul_f32 v[80:81], v[78:79], v[154:155] op_sel_hi:[1,0]
	v_cvt_pk_bf16_f32 v78, v86, v87
	v_cvt_pk_bf16_f32 v79, v88, v89
	s_nop 0
	v_cvt_pk_bf16_f32 v80, v80, v81
	v_cvt_pk_bf16_f32 v81, v90, v91
	global_store_dwordx4 v[94:95], v[78:81], off offset:256
	s_nop 1
	v_lshlrev_b64 v[78:79], 12, v[164:165]
	v_lshl_add_u64 v[78:79], v[180:181], 0, v[78:79]
	v_pk_mul_f32 v[80:81], v[84:85], v[152:153] op_sel_hi:[1,0]
	v_pk_mul_f32 v[84:85], v[76:77], v[152:153] op_sel_hi:[1,0]
	v_pk_mul_f32 v[76:77], v[74:75], v[152:153] op_sel_hi:[1,0]
	v_cvt_pk_bf16_f32 v74, v82, v83
	v_cvt_pk_bf16_f32 v75, v80, v81
	s_nop 0
	v_cvt_pk_bf16_f32 v76, v76, v77
	v_cvt_pk_bf16_f32 v77, v84, v85
	global_store_dwordx4 v[78:79], v[74:77], off
	s_nop 1
	v_pk_mul_f32 v[74:75], v[68:69], v[152:153] op_sel_hi:[1,0]
	v_pk_mul_f32 v[68:69], v[66:67], v[152:153] op_sel_hi:[1,0]
	v_cvt_pk_bf16_f32 v66, v70, v71
	v_cvt_pk_bf16_f32 v67, v72, v73
	s_nop 0
	v_cvt_pk_bf16_f32 v68, v68, v69
	v_cvt_pk_bf16_f32 v69, v74, v75
	global_store_dwordx4 v[78:79], v[66:69], off offset:256
	s_nop 1
	v_lshlrev_b64 v[66:67], 12, v[158:159]
	v_lshl_add_u64 v[66:67], v[180:181], 0, v[66:67]
	v_pk_mul_f32 v[68:69], v[60:61], v[148:149] op_sel_hi:[1,0]
	v_pk_mul_f32 v[60:61], v[58:59], v[148:149] op_sel_hi:[1,0]
	v_cvt_pk_bf16_f32 v58, v62, v63
	v_cvt_pk_bf16_f32 v59, v64, v65
	s_nop 0
	v_cvt_pk_bf16_f32 v60, v60, v61
	v_cvt_pk_bf16_f32 v61, v68, v69
	global_store_dwordx4 v[66:67], v[58:61], off
	s_nop 1
	v_pk_mul_f32 v[58:59], v[48:49], v[148:149] op_sel_hi:[1,0]
	v_pk_mul_f32 v[48:49], v[46:47], v[148:149] op_sel_hi:[1,0]
	v_cvt_pk_bf16_f32 v46, v54, v55
	v_cvt_pk_bf16_f32 v47, v56, v57
	s_nop 0
	v_cvt_pk_bf16_f32 v48, v48, v49
	v_cvt_pk_bf16_f32 v49, v58, v59
	global_store_dwordx4 v[66:67], v[46:49], off offset:256
	s_nop 1
	v_lshlrev_b64 v[46:47], 12, v[156:157]
	v_lshl_add_u64 v[46:47], v[180:181], 0, v[46:47]
	v_pk_mul_f32 v[48:49], v[52:53], v[144:145] op_sel_hi:[1,0]
	v_pk_mul_f32 v[52:53], v[44:45], v[144:145] op_sel_hi:[1,0]
	v_pk_mul_f32 v[44:45], v[42:43], v[144:145] op_sel_hi:[1,0]
	v_cvt_pk_bf16_f32 v42, v50, v51
	v_cvt_pk_bf16_f32 v43, v48, v49
	s_nop 0
	v_cvt_pk_bf16_f32 v44, v44, v45
	v_cvt_pk_bf16_f32 v45, v52, v53
	global_store_dwordx4 v[46:47], v[42:45], off
	s_nop 1
	v_pk_mul_f32 v[42:43], v[32:33], v[144:145] op_sel_hi:[1,0]
	v_pk_mul_f32 v[32:33], v[30:31], v[144:145] op_sel_hi:[1,0]
	v_cvt_pk_bf16_f32 v30, v38, v39
	v_cvt_pk_bf16_f32 v31, v40, v41
	s_nop 0
	v_cvt_pk_bf16_f32 v32, v32, v33
	v_cvt_pk_bf16_f32 v33, v42, v43
	global_store_dwordx4 v[46:47], v[30:33], off offset:256
	s_nop 1
	v_lshlrev_b64 v[30:31], 12, v[150:151]
	v_lshl_add_u64 v[30:31], v[180:181], 0, v[30:31]
	v_pk_mul_f32 v[32:33], v[36:37], v[142:143] op_sel_hi:[1,0]
	v_pk_mul_f32 v[36:37], v[28:29], v[142:143] op_sel_hi:[1,0]
	v_pk_mul_f32 v[28:29], v[26:27], v[142:143] op_sel_hi:[1,0]
	v_cvt_pk_bf16_f32 v26, v34, v35
	v_cvt_pk_bf16_f32 v27, v32, v33
	s_nop 0
	v_cvt_pk_bf16_f32 v28, v28, v29
	v_cvt_pk_bf16_f32 v29, v36, v37
	global_store_dwordx4 v[30:31], v[26:29], off
	s_nop 1
	v_pk_mul_f32 v[26:27], v[16:17], v[142:143] op_sel_hi:[1,0]
	v_pk_mul_f32 v[16:17], v[14:15], v[142:143] op_sel_hi:[1,0]
	v_cvt_pk_bf16_f32 v14, v22, v23
	v_cvt_pk_bf16_f32 v15, v24, v25
	s_nop 0
	v_cvt_pk_bf16_f32 v16, v16, v17
	v_cvt_pk_bf16_f32 v17, v26, v27
	global_store_dwordx4 v[30:31], v[14:17], off offset:256
	s_nop 1
	v_lshlrev_b64 v[14:15], 12, v[146:147]
	v_lshl_add_u64 v[14:15], v[180:181], 0, v[14:15]
	v_pk_mul_f32 v[16:17], v[20:21], v[172:173] op_sel_hi:[1,0]
	v_pk_mul_f32 v[20:21], v[12:13], v[172:173] op_sel_hi:[1,0]
	v_pk_mul_f32 v[12:13], v[10:11], v[172:173] op_sel_hi:[1,0]
	v_cvt_pk_bf16_f32 v10, v18, v19
	v_cvt_pk_bf16_f32 v11, v16, v17
	s_nop 0
	v_cvt_pk_bf16_f32 v12, v12, v13
	v_cvt_pk_bf16_f32 v13, v20, v21
	global_store_dwordx4 v[14:15], v[10:13], off
	s_nop 1
	v_pk_mul_f32 v[10:11], v[4:5], v[172:173] op_sel_hi:[1,0]
	v_pk_mul_f32 v[4:5], v[2:3], v[172:173] op_sel_hi:[1,0]
	v_cvt_pk_bf16_f32 v2, v6, v7
	v_cvt_pk_bf16_f32 v3, v8, v9
	s_nop 0
	v_cvt_pk_bf16_f32 v4, v4, v5
	v_cvt_pk_bf16_f32 v5, v10, v11
	global_store_dwordx4 v[14:15], v[2:5], off offset:256
